# w1 + GQA loop row sums via v_pk_add_f32 directly into running sums (64 add -> 32 pk_add)
# baseline (speedup 1.0000x reference)
;   #define DMA_K(t,slot) glds16(ksrc+(long)(t)*KVBLK*kp,(unsigned)__builtin_amdgcn_readfirstlane(kdst+(slot)))
;   #define DMA_V(t,slot) glds16(vsrc+(long)(t)*KVBLK*vp,(unsigned)__builtin_amdgcn_readfirstlane(vdst+(slot)))
;   #define DMA_K(t,slot) glds16(ksrc+(long)(t)*KVBLK*kp,(unsigned)__builtin_amdgcn_readfirstlane(kdst+(slot)))
;   #define DMA_V(t,slot) glds16(vsrc+(long)(t)*KVBLK*vp,(unsigned)__builtin_amdgcn_readfirstlane(vdst+(slot)))
;   #define MF(k,q,c) __builtin_amdgcn_mfma_f32_32x32x16_bf16(k,q,c,0,0,0)
;   #define DMA_K(t,slot) glds16(ksrc+(long)(t)*KVBLK*kp,(unsigned)__builtin_amdgcn_readfirstlane(kdst+(slot)))
; __device__ __forceinline__ void attn_unit2(const bf16*Qu,int qp,const bf16*__restrict__ Kh,int kp,const bf16*__restrict__ Vh,int vp,bf16*Ou,int op,int NT,char*shm,int tid_in){
;   int tid_=tid_in; asm volatile("":"+v"(tid_));
;   const int tid=tid_,lane=tid&63,r32=lane&31,hi=lane>>5; const int wid=__builtin_amdgcn_readfirstlane(tid>>6);
;   const bf16*Qw=Qu+(long)(wid*64)*qp;
;   const unsigned lds0=(unsigned)(uintptr_t)shm;
;   float*wsf=(float*)(shm+U2_WS)+wid*64;
;   const bf16*ksrc=Kh+(long)lane*kp+wid*8;
;   const bf16*vsrc=Vh+(long)(16*(wid&3)+(lane>>2))*vp+(wid>>2)*32+(lane&3)*8;
;   const unsigned kdst=lds0+U2_K+wid*1024, vdst=lds0+U2_V+wid*1024;
;     ...
;   const lds_cptr shm3=(lds_cptr)shm; const lds_cptr kp0=shm3+U2_K+hi*1024+r32*16; const lds_cptr vp0=shm3+U2_V+((lane>>4)&1)*32+(lane&3)*8+(4*hi+((lane&15)>>2))*64;
;   DMA_K(0,0);DMA_V(0,0);DMA_K(1,SLOTB);DMA_V(1,SLOTB);DMA_K(2,2*SLOTB);DMA_V(2,2*SLOTB);
;   bf16x8 qa[4],qb[4];
;   #pragma unroll
;   for(int d0=0;d0<4;++d0){qa[d0]=*reinterpret_cast<const bf16x8*>(&Qw[(long)r32*qp+d0*16+hi*8]);qb[d0]=*reinterpret_cast<const bf16x8*>(&Qw[(long)(32+r32)*qp+d0*16+hi*8]);}
;   float la=0.f,lb=0.f; f32x16 oa[2],ob[2]; oa[0]=f32x16{};oa[1]=f32x16{};ob[0]=f32x16{};ob[1]=f32x16{};
;   asm volatile("s_waitcnt vmcnt(0) lgkmcnt(0)\n\ts_barrier":::"memory");
;   int sl_cur=0,sl_n1=SLOTB,sl_n3=3*SLOTB;
;   bf16x8 kf[8]; kload8(kf,kp0);
;   f32x16 a0,a1,b0,b1; const f32x16 z16=f32x16{}; u32x4 pa[4],pb[4];
;     ...
;   #pragma unroll
;   for(int d0=0;d0<4;++d0){ a0=MF(kf[2*d0],qa[d0],d0==0?z16:a0); a1=MF(kf[2*d0+1],qa[d0],d0==0?z16:a1); }
.LBB0_894:
	s_and_b64 vcc, exec, s[2:3]
	s_cbranch_vccz .LBB0_923
	s_ashr_i32 s2, s72, 7
	s_ashr_i32 s3, s2, 31
	s_lshl_b32 s4, s72, 18
	s_and_b32 s6, s4, 0x3c0000
	s_lshl_b64 s[4:5], s[2:3], 22
	s_or_b32 s4, s4, s6
	s_bfe_u32 s8, s72, 0x30004
	s_lshl_b64 s[6:7], s[4:5], 1
	s_add_u32 s3, s43, s6
	s_addc_u32 s4, s44, s7
	s_lshl_b32 s10, s8, 6
	s_lshl_b32 s5, s8, 7
	s_add_u32 s14, s3, s5
	s_addc_u32 s15, s4, 0
	s_mul_hi_i32 s3, s2, 0x210000
	s_mul_i32 s2, s2, 0x210000
	s_add_u32 s4, s52, s2
	s_addc_u32 s5, s53, s3
	s_and_b32 s8, s72, 64
	s_lshl_b32 s11, s8, 1
	s_add_u32 s8, s4, s11
	s_addc_u32 s9, s5, 0
	s_add_u32 s2, s45, s2
	s_addc_u32 s3, s46, s3
	s_add_u32 s12, s2, s11
	v_readlane_b32 s2, v253, 6
	v_mbcnt_lo_u32_b32 v0, -1, 0
	v_mbcnt_hi_u32_b32 v0, -1, v0
	s_addc_u32 s13, s3, 0
	v_mov_b32_e32 v239, 0x260
	s_waitcnt vmcnt(9)
	v_or_b32_e32 v42, s2, v0
	s_nop 0
	v_readfirstlane_b32 s16, v42
	s_and_b32 s2, s16, 0xffffffc0
	s_ashr_i32 s3, s2, 31
	v_and_b32_e32 v249, 63, v42
	s_ashr_i32 s11, s16, 6
	s_lshl_b64 s[4:5], s[2:3], 10
	s_add_u32 s14, s14, s4
	v_lshlrev_b32_e32 v0, 8, v249
	s_addc_u32 s15, s15, s5
	v_lshl_add_u64 v[2:3], s[8:9], 0, v[0:1]
	s_lshl_b32 s8, s11, 3
	s_lshl_b32 s3, s11, 4
	v_bfe_u32 v0, v42, 2, 4
	s_ashr_i32 s9, s8, 31
	v_and_or_b32 v0, s3, 48, v0
	s_ashr_i32 s3, s16, 3
	v_lshl_add_u64 v[98:99], s[8:9], 1, v[2:3]
	s_and_b32 s8, s3, 0xffffffe0
	v_lshlrev_b32_e32 v0, 8, v0
	s_ashr_i32 s9, s8, 31
	s_lshl_b32 s3, s11, 10
	v_lshl_add_u64 v[2:3], s[12:13], 0, v[0:1]
	v_lshlrev_b32_e32 v248, 3, v42
	s_cmp_lg_u32 0, -1
	v_lshl_add_u64 v[2:3], s[8:9], 1, v[2:3]
	v_and_b32_e32 v43, 24, v248
	s_cselect_b32 s8, 0, 0
	v_lshlrev_b32_e32 v0, 1, v43
	s_add_i32 s3, s3, s8
	s_mov_b32 s8, m0
	s_mov_b32 m0, s3
	s_nop 0
	global_load_lds_dwordx4 v[98:99], off
	s_mov_b32 m0, s8
	v_lshl_add_u64 v[100:101], v[2:3], 0, v[0:1]
	s_add_i32 s12, s3, 0x8000
	s_mov_b32 s8, m0
	s_mov_b32 m0, s12
	s_nop 0
	global_load_lds_dwordx4 v[100:101], off
	s_mov_b32 m0, s8
	s_mov_b64 s[16:17], 0x4000
	v_lshl_add_u64 v[2:3], v[98:99], 0, s[16:17]
	s_add_i32 s8, s3, 0x2000
	s_mov_b32 s9, m0
	s_mov_b32 m0, s8
	s_nop 0
	global_load_lds_dwordx4 v[2:3], off
	s_mov_b32 m0, s9
	v_and_b32_e32 v251, 31, v42
	v_lshl_add_u64 v[2:3], v[100:101], 0, s[16:17]
	s_add_i32 s8, s3, 0xa000
	s_mov_b32 s9, m0
	s_mov_b32 m0, s8
	s_nop 0
	global_load_lds_dwordx4 v[2:3], off
	s_mov_b32 m0, s9
	s_mov_b64 s[16:17], 0x8000
	v_bfe_u32 v238, v42, 5, 1
	v_lshl_add_u64 v[2:3], v[98:99], 0, s[16:17]
	s_add_i32 s8, s3, 0x4000
	s_mov_b32 s9, m0
	s_mov_b32 m0, s8
	s_nop 0
	global_load_lds_dwordx4 v[2:3], off
	s_mov_b32 m0, s9
	v_lshlrev_b32_e32 v0, 10, v251
	v_lshl_add_u64 v[2:3], v[100:101], 0, s[16:17]
	s_add_i32 s8, s3, 0xc000
	s_mov_b32 s9, m0
	s_mov_b32 m0, s8
	s_nop 0
	global_load_lds_dwordx4 v[2:3], off
	s_mov_b32 m0, s9
	v_lshl_or_b32 v0, v238, 4, v0
	global_load_dwordx4 v[170:173], v0, s[14:15]
	global_load_dwordx4 v[174:177], v0, s[14:15] offset:32
	global_load_dwordx4 v[178:181], v0, s[14:15] offset:64
	global_load_dwordx4 v[182:185], v0, s[14:15] offset:96
	v_lshlrev_b32_e32 v2, 10, v238
	v_lshlrev_b32_e32 v3, 4, v251
	v_add3_u32 v241, 0, v2, v3
	v_lshl_add_u64 v[2:3], s[14:15], 0, v[0:1]
	v_add_co_u32_e32 v2, vcc, s33, v2
	v_lshlrev_b32_e32 v0, 1, v42
	s_nop 0
	v_addc_co_u32_e32 v3, vcc, 0, v3, vcc
	global_load_dwordx4 v[150:153], v[2:3], off
	global_load_dwordx4 v[146:149], v[2:3], off offset:32
	global_load_dwordx4 v[142:145], v[2:3], off offset:64
	global_load_dwordx4 v[130:133], v[2:3], off offset:96
	s_waitcnt vmcnt(0) lgkmcnt(0)
	s_barrier
	ds_read_b128 v[34:37], v241
	ds_read_b128 v[38:41], v241 offset:512
	ds_read_b128 v[66:69], v241 offset:2048
	ds_read_b128 v[70:73], v241 offset:2560
	ds_read_b128 v[74:77], v241 offset:4096
	ds_read_b128 v[78:81], v241 offset:4608
	ds_read_b128 v[82:85], v241 offset:6144
	ds_read_b128 v[86:89], v241 offset:6656
	v_and_b32_e32 v0, 32, v0
	v_add3_u32 v0, 0, v0, v43
	s_mov_b64 s[8:9], 0xc000
	v_lshlrev_b32_e32 v42, 4, v42
	v_lshlrev_b32_e32 v44, 8, v238
	v_and_b32_e32 v42, 0xc0, v42
	s_mov_b32 s13, 1
	s_mov_b32 s15, 0
	s_movk_i32 s14, 0x2000
	s_movk_i32 s16, 0x4000
	v_add3_u32 v0, v0, v44, v42
	s_waitcnt vmcnt(7) lgkmcnt(7)
	v_mfma_f32_32x32x16_bf16 v[2:17], v[34:37], v[170:173], 0
	s_waitcnt lgkmcnt(6)
	v_mfma_f32_32x32x16_bf16 v[18:33], v[38:41], v[170:173], 0
	s_waitcnt vmcnt(6) lgkmcnt(5)
	v_mfma_f32_32x32x16_bf16 v[2:17], v[66:69], v[174:177], v[2:17]
	s_waitcnt lgkmcnt(4)
	v_mfma_f32_32x32x16_bf16 v[18:33], v[70:73], v[174:177], v[18:33]
	s_waitcnt vmcnt(5) lgkmcnt(3)
	v_mfma_f32_32x32x16_bf16 v[2:17], v[74:77], v[178:181], v[2:17]
	s_waitcnt lgkmcnt(2)
	v_mfma_f32_32x32x16_bf16 v[18:33], v[78:81], v[178:181], v[18:33]
	s_waitcnt vmcnt(4) lgkmcnt(1)
	v_mfma_f32_32x32x16_bf16 v[2:17], v[82:85], v[182:185], v[2:17]
	s_waitcnt lgkmcnt(0)
;   #define DMA_K(t,slot) glds16(ksrc+(long)(t)*KVBLK*kp,(unsigned)__builtin_amdgcn_readfirstlane(kdst+(slot)))
;   #define DMA_V(t,slot) glds16(vsrc+(long)(t)*KVBLK*vp,(unsigned)__builtin_amdgcn_readfirstlane(vdst+(slot)))
;   #define DMA_K(t,slot) glds16(ksrc+(long)(t)*KVBLK*kp,(unsigned)__builtin_amdgcn_readfirstlane(kdst+(slot)))
;   #define DMA_V(t,slot) glds16(vsrc+(long)(t)*KVBLK*vp,(unsigned)__builtin_amdgcn_readfirstlane(vdst+(slot)))
;   #define MF(k,q,c) __builtin_amdgcn_mfma_f32_32x32x16_bf16(k,q,c,0,0,0)
;   #define X4(P,B) do{ P[B]=__builtin_amdgcn_exp2f(P[B]); P[B+1]=__builtin_amdgcn_exp2f(P[B+1]); P[B+2]=__builtin_amdgcn_exp2f(P[B+2]); P[B+3]=__builtin_amdgcn_exp2f(P[B+3]); asm volatile("":"+v"(P)); SBAR(); }while(0)
;   #define SP4(SUM,P,B,PW,H) do{ SUM+=P[B]; SUM+=P[B+1]; SUM+=P[B+2]; SUM+=P[B+3]; asm volatile("":"+v"(SUM)); PW[(H)*2]=cvtpk_s(P[B],P[B+1]); PW[(H)*2+1]=cvtpk_s(P[B+2],P[B+3]); asm volatile("":"+v"(PW)); SBAR(); }while(0)
; __device__ __forceinline__ void attn_unit2(const bf16*Qu,int qp,const bf16*__restrict__ Kh,int kp,const bf16*__restrict__ Vh,int vp,bf16*Ou,int op,int NT,char*shm,int tid_in){
;     ...
;   for(int d0=0;d0<4;++d0){ a0=MF(kf[2*d0],qa[d0],d0==0?z16:a0); a1=MF(kf[2*d0+1],qa[d0],d0==0?z16:a1); }
;   #pragma unroll
;   for(int r=0;r<16;++r){a0[r]=__builtin_amdgcn_exp2f(a0[r]);a1[r]=__builtin_amdgcn_exp2f(a1[r]);}
;   for(int t=0;t<NT;++t){
;     if(t>0){ if(t+2<NT) asm volatile("s_waitcnt vmcnt(2) lgkmcnt(0)\n\ts_barrier":::"memory"); else asm volatile("s_waitcnt vmcnt(0) lgkmcnt(0)\n\ts_barrier":::"memory"); }
;     if(t+3<NT){DMA_K(t+3,sl_n3);DMA_V(t+3,sl_n3);}
;     const bool nx=t+1<NT; const lds_cptr vq=vp0+sl_cur; s16x4 vlo[8],vhi[8]; float sa=0.f,sb=0.f;
;     ...
;     b0=MF(kf[0],qb[0],z16); SP4(sa,a0,0,pa[0],0);  b1=MF(kf[1],qb[0],z16); SP4(sa,a0,4,pa[0],1);
;     b0=MF(kf[2],qb[1],b0);  SP4(sa,a0,8,pa[1],0);  b1=MF(kf[3],qb[1],b1);  SP4(sa,a0,12,pa[1],1);
;     b0=MF(kf[4],qb[2],b0);  SP4(sa,a1,0,pa[2],0);  b1=MF(kf[5],qb[2],b1);  SP4(sa,a1,4,pa[2],1);
;     b0=MF(kf[6],qb[3],b0);  SP4(sa,a1,8,pa[3],0);  b1=MF(kf[7],qb[3],b1);  SP4(sa,a1,12,pa[3],1);
;     la+=sa;
;     VLD(); if(nx) kload8(kf,kp0+sl_n1);
;     ...
;     PVA(0,0); X4(b0,0); PVA(0,1); X4(b0,4); PVA(1,0); X4(b0,8); PVA(1,1); X4(b0,12);
;     PVA(2,0); X4(b1,0); PVA(2,1); X4(b1,4); PVA(3,0); X4(b1,8); PVA(3,1); X4(b1,12);
	v_mfma_f32_32x32x16_bf16 v[18:33], v[86:89], v[182:185], v[18:33]
	s_nop 9
	v_exp_f32_e32 v43, v2
	v_exp_f32_e32 v45, v3
	v_exp_f32_e32 v46, v4
	v_exp_f32_e32 v47, v5
	v_lshl_add_u64 v[2:3], v[100:101], 0, s[8:9]
	v_lshl_add_u64 v[4:5], v[98:99], 0, s[8:9]
	s_add_i32 s8, s3, 0x6000
	s_mov_b32 s9, m0
	s_mov_b32 m0, s8
	s_nop 0
	global_load_lds_dwordx4 v[4:5], off
	s_mov_b32 m0, s9
	v_exp_f32_e32 v18, v18
	v_exp_f32_e32 v19, v19
	v_exp_f32_e32 v20, v20
	v_exp_f32_e32 v21, v21
	v_exp_f32_e32 v6, v6
	v_exp_f32_e32 v22, v22
	v_exp_f32_e32 v7, v7
	v_exp_f32_e32 v23, v23
	v_exp_f32_e32 v8, v8
	v_exp_f32_e32 v24, v24
	v_exp_f32_e32 v9, v9
	v_exp_f32_e32 v25, v25
	v_exp_f32_e32 v10, v10
	v_exp_f32_e32 v26, v26
	v_exp_f32_e32 v11, v11
	v_exp_f32_e32 v27, v27
	v_exp_f32_e32 v12, v12
	v_exp_f32_e32 v28, v28
	v_exp_f32_e32 v13, v13
	v_exp_f32_e32 v29, v29
	v_exp_f32_e32 v14, v14
	v_exp_f32_e32 v30, v30
	v_exp_f32_e32 v15, v15
	v_exp_f32_e32 v31, v31
	v_exp_f32_e32 v16, v16
	v_exp_f32_e32 v32, v32
	v_exp_f32_e32 v17, v17
	v_exp_f32_e32 v33, v33
	s_add_i32 s8, s3, 0xe000
	s_mov_b32 s9, m0
	s_mov_b32 m0, s8
	s_nop 0
	global_load_lds_dwordx4 v[2:3], off
	s_mov_b32 m0, s9
	v_add_f32_e32 v2, 0, v43
	v_add_f32_e32 v2, v45, v2
	v_add_f32_e32 v2, v46, v2
	v_add_f32_e32 v2, v47, v2
	v_cvt_pk_bf16_f32 v158, v43, v45
	v_cvt_pk_bf16_f32 v159, v46, v47
	s_nop 0
	v_add_f32_e32 v2, v6, v2
	v_add_f32_e32 v2, v7, v2
	v_add_f32_e32 v2, v8, v2
	v_add_f32_e32 v2, v9, v2
	v_cvt_pk_bf16_f32 v160, v6, v7
	v_cvt_pk_bf16_f32 v161, v8, v9
	s_nop 0
	v_add_f32_e32 v2, v10, v2
	v_add_f32_e32 v2, v11, v2
	v_add_f32_e32 v2, v12, v2
	v_add_f32_e32 v2, v13, v2
	v_cvt_pk_bf16_f32 v154, v10, v11
	v_cvt_pk_bf16_f32 v155, v12, v13
	s_nop 0
	v_add_f32_e32 v2, v14, v2
	v_add_f32_e32 v2, v15, v2
	v_add_f32_e32 v2, v16, v2
	v_add_f32_e32 v2, v17, v2
	v_cvt_pk_bf16_f32 v156, v14, v15
	v_cvt_pk_bf16_f32 v157, v16, v17
	s_nop 0
	v_add_f32_e32 v2, v18, v2
	v_add_f32_e32 v2, v19, v2
	v_add_f32_e32 v2, v20, v2
	v_add_f32_e32 v2, v21, v2
	v_cvt_pk_bf16_f32 v138, v18, v19
	v_cvt_pk_bf16_f32 v139, v20, v21
	s_nop 0
	v_add_f32_e32 v2, v22, v2
	v_add_f32_e32 v2, v23, v2
	v_add_f32_e32 v2, v24, v2
	v_add_f32_e32 v2, v25, v2
	v_cvt_pk_bf16_f32 v140, v22, v23
	v_cvt_pk_bf16_f32 v141, v24, v25
	s_nop 0
	v_add_f32_e32 v2, v26, v2
	v_add_f32_e32 v2, v27, v2
	v_add_f32_e32 v2, v28, v2
	v_add_f32_e32 v2, v29, v2
	v_cvt_pk_bf16_f32 v134, v26, v27
	v_cvt_pk_bf16_f32 v135, v28, v29
	s_nop 0
	v_add_f32_e32 v2, v30, v2
	v_add_f32_e32 v2, v31, v2
	v_add_f32_e32 v2, v32, v2
	v_add_f32_e32 v102, v33, v2
	v_cvt_pk_bf16_f32 v136, v30, v31
	v_cvt_pk_bf16_f32 v137, v32, v33
	s_waitcnt vmcnt(3)
	v_mfma_f32_32x32x16_bf16 v[50:65], v[34:37], v[150:153], 0
	v_mfma_f32_32x32x16_bf16 v[34:49], v[38:41], v[150:153], 0
	s_waitcnt vmcnt(2)
	v_mfma_f32_32x32x16_bf16 v[50:65], v[66:69], v[146:149], v[50:65]
	ds_read_b64_tr_b16 v[2:3], v0 offset:32768
	ds_read_b64_tr_b16 v[4:5], v0 offset:33280
	ds_read_b64_tr_b16 v[66:67], v0 offset:33792
	ds_read_b64_tr_b16 v[68:69], v0 offset:34304
	v_mfma_f32_32x32x16_bf16 v[34:49], v[70:73], v[146:149], v[34:49]
	s_waitcnt vmcnt(1)
	v_mfma_f32_32x32x16_bf16 v[50:65], v[74:77], v[142:145], v[50:65]
	v_mfma_f32_32x32x16_bf16 v[34:49], v[78:81], v[142:145], v[34:49]
	ds_read_b64_tr_b16 v[70:71], v0 offset:34816
	ds_read_b64_tr_b16 v[72:73], v0 offset:35328
	ds_read_b64_tr_b16 v[74:75], v0 offset:35840
	ds_read_b64_tr_b16 v[76:77], v0 offset:36352
	ds_read_b64_tr_b16 v[18:19], v0 offset:36864
	ds_read_b64_tr_b16 v[20:21], v0 offset:37376
	ds_read_b64_tr_b16 v[78:79], v0 offset:37888
	ds_read_b64_tr_b16 v[80:81], v0 offset:38400
	s_waitcnt vmcnt(0)
	v_mfma_f32_32x32x16_bf16 v[50:65], v[82:85], v[130:133], v[50:65]
	ds_read_b64_tr_b16 v[82:83], v0 offset:38912
	ds_read_b64_tr_b16 v[84:85], v0 offset:39424
	ds_read_b64_tr_b16 v[90:91], v0 offset:39936
	ds_read_b64_tr_b16 v[92:93], v0 offset:40448
	ds_read_b128 v[206:209], v241 offset:8192
	ds_read_b128 v[210:213], v241 offset:8704
	ds_read_b128 v[202:205], v241 offset:10240
	ds_read_b128 v[198:201], v241 offset:10752
	ds_read_b128 v[222:225], v241 offset:12288
	ds_read_b128 v[218:221], v241 offset:12800
	ds_read_b128 v[214:217], v241 offset:14336
	ds_read_b128 v[194:197], v241 offset:14848
	v_exp_f32_e32 v50, v50
	v_mfma_f32_32x32x16_bf16 v[34:49], v[86:89], v[130:133], v[34:49]
	v_exp_f32_e32 v51, v51
	v_exp_f32_e32 v52, v52
	v_exp_f32_e32 v53, v53
	s_waitcnt lgkmcnt(14)
	v_mfma_f32_32x32x16_bf16 v[2:17], v[158:161], v[2:5], 0
	v_mfma_f32_32x32x16_bf16 v[18:33], v[158:161], v[18:21], 0
	v_exp_f32_e32 v54, v54
	v_exp_f32_e32 v55, v55
	v_exp_f32_e32 v56, v56
	v_exp_f32_e32 v57, v57
	v_mfma_f32_32x32x16_bf16 v[2:17], v[154:157], v[66:69], v[2:17]
	v_exp_f32_e32 v58, v58
	v_exp_f32_e32 v59, v59
	v_exp_f32_e32 v60, v60
	v_exp_f32_e32 v61, v61
	s_waitcnt lgkmcnt(12)
	v_mfma_f32_32x32x16_bf16 v[18:33], v[154:157], v[78:81], v[18:33]
	v_exp_f32_e32 v62, v62
	v_exp_f32_e32 v63, v63
	v_exp_f32_e32 v64, v64
	v_exp_f32_e32 v65, v65
	v_mfma_f32_32x32x16_bf16 v[2:17], v[138:141], v[70:73], v[2:17]
	v_exp_f32_e32 v34, v34
	v_exp_f32_e32 v35, v35
	v_exp_f32_e32 v36, v36
	v_exp_f32_e32 v37, v37
	s_waitcnt lgkmcnt(10)
	v_mfma_f32_32x32x16_bf16 v[18:33], v[138:141], v[82:85], v[18:33]
	v_exp_f32_e32 v38, v38
	v_exp_f32_e32 v39, v39
	v_exp_f32_e32 v40, v40
	v_exp_f32_e32 v41, v41
	v_mfma_f32_32x32x16_bf16 v[2:17], v[134:137], v[74:77], v[2:17]
	v_exp_f32_e32 v42, v42
	v_exp_f32_e32 v43, v43
	v_exp_f32_e32 v44, v44
	v_exp_f32_e32 v45, v45
	s_waitcnt lgkmcnt(8)
	v_mfma_f32_32x32x16_bf16 v[18:33], v[134:137], v[90:93], v[18:33]
	v_exp_f32_e32 v46, v46
	v_exp_f32_e32 v47, v47
	v_exp_f32_e32 v48, v48
	v_exp_f32_e32 v49, v49
	s_waitcnt lgkmcnt(7)
; #define SBAR() __builtin_amdgcn_sched_barrier(0)
;   #define MF(k,q,c) __builtin_amdgcn_mfma_f32_32x32x16_bf16(k,q,c,0,0,0)
;   #define X4(P,B) do{ P[B]=__builtin_amdgcn_exp2f(P[B]); P[B+1]=__builtin_amdgcn_exp2f(P[B+1]); P[B+2]=__builtin_amdgcn_exp2f(P[B+2]); P[B+3]=__builtin_amdgcn_exp2f(P[B+3]); asm volatile("":"+v"(P)); SBAR(); }while(0)
;   #define SP4(SUM,P,B,PW,H) do{ SUM+=P[B]; SUM+=P[B+1]; SUM+=P[B+2]; SUM+=P[B+3]; asm volatile("":"+v"(SUM)); PW[(H)*2]=cvtpk_s(P[B],P[B+1]); PW[(H)*2+1]=cvtpk_s(P[B+2],P[B+3]); asm volatile("":"+v"(PW)); SBAR(); }while(0)
;     #define VLD() do{ _Pragma("unroll") for(int i=0;i<8;++i){ vlo[i]=vtr(vq+((i>>2)*4096+(i&3)*1024)); vhi[i]=vtr(vq+((i>>2)*4096+(i&3)*1024+512)); } }while(0)
;     #define PVB(ks,d0) ob[d0]=MF(__builtin_bit_cast(bf16x8,pb[ks]),VF((ks)+4*(d0)),ob[d0])
; __device__ __forceinline__ void attn_unit2(const bf16*Qu,int qp,const bf16*__restrict__ Kh,int kp,const bf16*__restrict__ Vh,int vp,bf16*Ou,int op,int NT,char*shm,int tid_in){
;     ...
;     if(nx){ a0=MF(kf[0],qa[0],z16); } SP4(sb,b0,0,pb[0],0);  if(nx){ a1=MF(kf[1],qa[0],z16); } SP4(sb,b0,4,pb[0],1);
;     if(nx){ a0=MF(kf[2],qa[1],a0); }  SP4(sb,b0,8,pb[1],0);  if(nx){ a1=MF(kf[3],qa[1],a1); }  SP4(sb,b0,12,pb[1],1);
;     if(nx){ a0=MF(kf[4],qa[2],a0); }  SP4(sb,b1,0,pb[2],0);  if(nx){ a1=MF(kf[5],qa[2],a1); }  SP4(sb,b1,4,pb[2],1);
;     if(nx){ a0=MF(kf[6],qa[3],a0); }  SP4(sb,b1,8,pb[3],0);  if(nx){ a1=MF(kf[7],qa[3],a1); }  SP4(sb,b1,12,pb[3],1);
;     lb+=sb;
;     VLD(); SBAR();
;     PVB(0,0); if(nx) X4(a0,0); PVB(0,1); if(nx) X4(a0,4); PVB(1,0); if(nx) X4(a0,8); PVB(1,1); if(nx) X4(a0,12);
;     PVB(2,0); if(nx) X4(a1,0); PVB(2,1); if(nx) X4(a1,4); PVB(3,0); if(nx) X4(a1,8); PVB(3,1); if(nx) X4(a1,12);
	v_mfma_f32_32x32x16_bf16 v[82:97], v[206:209], v[170:173], 0
	v_add_f32_e32 v66, 0, v50
	v_add_f32_e32 v66, v51, v66
	v_add_f32_e32 v66, v52, v66
	v_add_f32_e32 v66, v53, v66
	v_cvt_pk_bf16_f32 v162, v50, v51
	v_cvt_pk_bf16_f32 v163, v52, v53
	s_nop 0
	v_add_f32_e32 v50, v54, v66
	s_waitcnt lgkmcnt(6)
	v_mfma_f32_32x32x16_bf16 v[66:81], v[210:213], v[170:173], 0
	v_add_f32_e32 v50, v55, v50
	v_add_f32_e32 v50, v56, v50
	v_add_f32_e32 v50, v57, v50
	v_cvt_pk_bf16_f32 v164, v54, v55
	v_cvt_pk_bf16_f32 v165, v56, v57
	s_waitcnt lgkmcnt(5)
	v_mfma_f32_32x32x16_bf16 v[82:97], v[202:205], v[174:177], v[82:97]
	v_add_f32_e32 v50, v58, v50
	v_add_f32_e32 v50, v59, v50
	v_add_f32_e32 v50, v60, v50
	v_add_f32_e32 v50, v61, v50
	v_cvt_pk_bf16_f32 v166, v58, v59
	v_cvt_pk_bf16_f32 v167, v60, v61
	s_waitcnt lgkmcnt(4)
	v_mfma_f32_32x32x16_bf16 v[66:81], v[198:201], v[174:177], v[66:81]
	v_add_f32_e32 v50, v62, v50
	v_add_f32_e32 v50, v63, v50
	v_add_f32_e32 v50, v64, v50
	v_add_f32_e32 v50, v65, v50
	v_cvt_pk_bf16_f32 v168, v62, v63
	v_cvt_pk_bf16_f32 v169, v64, v65
	s_waitcnt lgkmcnt(3)
	v_mfma_f32_32x32x16_bf16 v[82:97], v[222:225], v[178:181], v[82:97]
	v_add_f32_e32 v50, v34, v50
	v_add_f32_e32 v50, v35, v50
	v_add_f32_e32 v50, v36, v50
	v_add_f32_e32 v50, v37, v50
	v_cvt_pk_bf16_f32 v186, v34, v35
	v_cvt_pk_bf16_f32 v187, v36, v37
	s_waitcnt lgkmcnt(2)
	v_mfma_f32_32x32x16_bf16 v[66:81], v[218:221], v[178:181], v[66:81]
	v_add_f32_e32 v34, v38, v50
	v_add_f32_e32 v34, v39, v34
	v_add_f32_e32 v34, v40, v34
	v_add_f32_e32 v34, v41, v34
	v_cvt_pk_bf16_f32 v188, v38, v39
	v_cvt_pk_bf16_f32 v189, v40, v41
	s_waitcnt lgkmcnt(1)
	v_mfma_f32_32x32x16_bf16 v[82:97], v[214:217], v[182:185], v[82:97]
	v_add_f32_e32 v34, v42, v34
	v_add_f32_e32 v34, v43, v34
	v_add_f32_e32 v34, v44, v34
	v_add_f32_e32 v34, v45, v34
	v_cvt_pk_bf16_f32 v190, v42, v43
	v_cvt_pk_bf16_f32 v191, v44, v45
	s_waitcnt lgkmcnt(0)
	v_mfma_f32_32x32x16_bf16 v[66:81], v[194:197], v[182:185], v[66:81]
	v_add_f32_e32 v34, v46, v34
	v_add_f32_e32 v34, v47, v34
	v_add_f32_e32 v34, v48, v34
	v_add_f32_e32 v103, v49, v34
	v_cvt_pk_bf16_f32 v192, v46, v47
	v_cvt_pk_bf16_f32 v193, v48, v49
	ds_read_b64_tr_b16 v[34:35], v0 offset:32768
	ds_read_b64_tr_b16 v[36:37], v0 offset:33280
	ds_read_b64_tr_b16 v[104:105], v0 offset:33792
	ds_read_b64_tr_b16 v[106:107], v0 offset:34304
	ds_read_b64_tr_b16 v[108:109], v0 offset:34816
	ds_read_b64_tr_b16 v[110:111], v0 offset:35328
	ds_read_b64_tr_b16 v[112:113], v0 offset:35840
	ds_read_b64_tr_b16 v[114:115], v0 offset:36352
	ds_read_b64_tr_b16 v[50:51], v0 offset:36864
	ds_read_b64_tr_b16 v[52:53], v0 offset:37376
	ds_read_b64_tr_b16 v[116:117], v0 offset:37888
	ds_read_b64_tr_b16 v[118:119], v0 offset:38400
	ds_read_b64_tr_b16 v[120:121], v0 offset:38912
	ds_read_b64_tr_b16 v[122:123], v0 offset:39424
	ds_read_b64_tr_b16 v[124:125], v0 offset:39936
	ds_read_b64_tr_b16 v[126:127], v0 offset:40448
	v_mov_b32_e32 v226, v102
	v_mov_b32_e32 v227, 0
	v_mov_b32_e32 v232, v103
	v_mov_b32_e32 v233, 0
	s_waitcnt lgkmcnt(14)
	v_mfma_f32_32x32x16_bf16 v[34:49], v[162:165], v[34:37], 0
	v_exp_f32_e32 v82, v82
	v_exp_f32_e32 v83, v83
	v_exp_f32_e32 v84, v84
	v_exp_f32_e32 v85, v85
	s_waitcnt lgkmcnt(6)
	v_mfma_f32_32x32x16_bf16 v[50:65], v[162:165], v[50:53], 0
	v_exp_f32_e32 v86, v86
	v_exp_f32_e32 v87, v87
	v_exp_f32_e32 v88, v88
	v_exp_f32_e32 v89, v89
	v_mfma_f32_32x32x16_bf16 v[34:49], v[166:169], v[104:107], v[34:49]
	v_exp_f32_e32 v90, v90
	v_exp_f32_e32 v91, v91
	v_exp_f32_e32 v92, v92
	v_exp_f32_e32 v93, v93
	s_waitcnt lgkmcnt(4)
	v_mfma_f32_32x32x16_bf16 v[50:65], v[166:169], v[116:119], v[50:65]
	v_exp_f32_e32 v94, v94
	v_exp_f32_e32 v95, v95
	v_exp_f32_e32 v96, v96
	v_exp_f32_e32 v97, v97
	v_mfma_f32_32x32x16_bf16 v[34:49], v[186:189], v[108:111], v[34:49]
	v_exp_f32_e32 v66, v66
	v_exp_f32_e32 v67, v67
	v_exp_f32_e32 v68, v68
	v_exp_f32_e32 v69, v69
	s_waitcnt lgkmcnt(2)
	v_mfma_f32_32x32x16_bf16 v[50:65], v[186:189], v[120:123], v[50:65]
	v_exp_f32_e32 v70, v70
	v_exp_f32_e32 v71, v71
	v_exp_f32_e32 v72, v72
	v_exp_f32_e32 v73, v73
	v_mfma_f32_32x32x16_bf16 v[34:49], v[190:193], v[112:115], v[34:49]
	v_exp_f32_e32 v74, v74
	v_exp_f32_e32 v75, v75
	v_exp_f32_e32 v76, v76
	v_exp_f32_e32 v77, v77
	s_waitcnt lgkmcnt(0)
	v_mfma_f32_32x32x16_bf16 v[50:65], v[190:193], v[124:127], v[50:65]
	v_exp_f32_e32 v78, v78
	v_exp_f32_e32 v79, v79
	v_exp_f32_e32 v80, v80
	v_exp_f32_e32 v81, v81
	s_mov_b64 s[8:9], 0x10000
	v_lshl_add_u64 v[228:229], v[98:99], 0, s[8:9]
	v_lshl_add_u64 v[230:231], v[100:101], 0, s[8:9]
	s_branch .LBB0_897
;   #define MF(k,q,c) __builtin_amdgcn_mfma_f32_32x32x16_bf16(k,q,c,0,0,0)
;   #define X4(P,B) do{ P[B]=__builtin_amdgcn_exp2f(P[B]); P[B+1]=__builtin_amdgcn_exp2f(P[B+1]); P[B+2]=__builtin_amdgcn_exp2f(P[B+2]); P[B+3]=__builtin_amdgcn_exp2f(P[B+3]); asm volatile("":"+v"(P)); SBAR(); }while(0)
;   #define SP4(SUM,P,B,PW,H) do{ SUM+=P[B]; SUM+=P[B+1]; SUM+=P[B+2]; SUM+=P[B+3]; asm volatile("":"+v"(SUM)); PW[(H)*2]=cvtpk_s(P[B],P[B+1]); PW[(H)*2+1]=cvtpk_s(P[B+2],P[B+3]); asm volatile("":"+v"(PW)); SBAR(); }while(0)
;     #define VLD() do{ _Pragma("unroll") for(int i=0;i<8;++i){ vlo[i]=vtr(vq+((i>>2)*4096+(i&3)*1024)); vhi[i]=vtr(vq+((i>>2)*4096+(i&3)*1024+512)); } }while(0)
;     #define PVA(ks,d0) oa[d0]=MF(__builtin_bit_cast(bf16x8,pa[ks]),VF((ks)+4*(d0)),oa[d0])
; __device__ __forceinline__ void attn_unit2(const bf16*Qu,int qp,const bf16*__restrict__ Kh,int kp,const bf16*__restrict__ Vh,int vp,bf16*Ou,int op,int NT,char*shm,int tid_in){
;     ...
;     b0=MF(kf[0],qb[0],z16); SP4(sa,a0,0,pa[0],0);  b1=MF(kf[1],qb[0],z16); SP4(sa,a0,4,pa[0],1);
;     b0=MF(kf[2],qb[1],b0);  SP4(sa,a0,8,pa[1],0);  b1=MF(kf[3],qb[1],b1);  SP4(sa,a0,12,pa[1],1);
;     b0=MF(kf[4],qb[2],b0);  SP4(sa,a1,0,pa[2],0);  b1=MF(kf[5],qb[2],b1);  SP4(sa,a1,4,pa[2],1);
;     b0=MF(kf[6],qb[3],b0);  SP4(sa,a1,8,pa[3],0);  b1=MF(kf[7],qb[3],b1);  SP4(sa,a1,12,pa[3],1);
;     la+=sa;
;     VLD(); if(nx) kload8(kf,kp0+sl_n1);
;     ...
;     PVA(0,0); X4(b0,0); PVA(0,1); X4(b0,4); PVA(1,0); X4(b0,8); PVA(1,1); X4(b0,12);
;     PVA(2,0); X4(b1,0); PVA(2,1); X4(b1,4); PVA(3,0); X4(b1,8); PVA(3,1); X4(b1,12);
.LBB0_896:
	s_add_i32 s13, s13, 1
	v_add_u32_e32 v240, s14, v0
	v_mfma_f32_32x32x16_bf16 v[114:129], v[206:209], v[150:153], 0
	v_pk_add_f32 v[226:227], v[82:83], v[226:227]
	v_cvt_pk_bf16_f32 v158, v82, v83
	v_pk_add_f32 v[226:227], v[84:85], v[226:227]
	v_cvt_pk_bf16_f32 v159, v84, v85
	ds_read_b64_tr_b16 v[82:83], v240 offset:36864
	ds_read_b64_tr_b16 v[84:85], v240 offset:37376
	v_mfma_f32_32x32x16_bf16 v[98:113], v[210:213], v[150:153], 0
	v_pk_add_f32 v[226:227], v[86:87], v[226:227]
	v_cvt_pk_bf16_f32 v160, v86, v87
	v_pk_add_f32 v[226:227], v[88:89], v[226:227]
	v_cvt_pk_bf16_f32 v161, v88, v89
	ds_read_b64_tr_b16 v[86:87], v240 offset:37888
	ds_read_b64_tr_b16 v[88:89], v240 offset:38400
	v_mfma_f32_32x32x16_bf16 v[114:129], v[202:205], v[146:149], v[114:129]
	v_pk_add_f32 v[226:227], v[90:91], v[226:227]
	v_cvt_pk_bf16_f32 v154, v90, v91
	v_pk_add_f32 v[226:227], v[92:93], v[226:227]
	v_cvt_pk_bf16_f32 v155, v92, v93
	ds_read_b64_tr_b16 v[90:91], v240 offset:38912
	ds_read_b64_tr_b16 v[92:93], v240 offset:39424
	v_mfma_f32_32x32x16_bf16 v[98:113], v[198:201], v[146:149], v[98:113]
	v_pk_add_f32 v[226:227], v[94:95], v[226:227]
	v_cvt_pk_bf16_f32 v156, v94, v95
	v_pk_add_f32 v[226:227], v[96:97], v[226:227]
	v_cvt_pk_bf16_f32 v157, v96, v97
	ds_read_b64_tr_b16 v[94:95], v240 offset:39936
	ds_read_b64_tr_b16 v[96:97], v240 offset:40448
	v_mfma_f32_32x32x16_bf16 v[114:129], v[222:225], v[142:145], v[114:129]
	v_pk_add_f32 v[226:227], v[66:67], v[226:227]
	v_cvt_pk_bf16_f32 v138, v66, v67
	v_pk_add_f32 v[226:227], v[68:69], v[226:227]
	v_cvt_pk_bf16_f32 v139, v68, v69
	ds_read_b64_tr_b16 v[66:67], v240 offset:32768
	ds_read_b64_tr_b16 v[68:69], v240 offset:33280
	v_mfma_f32_32x32x16_bf16 v[98:113], v[218:221], v[142:145], v[98:113]
	v_pk_add_f32 v[226:227], v[70:71], v[226:227]
	v_cvt_pk_bf16_f32 v140, v70, v71
	v_pk_add_f32 v[226:227], v[72:73], v[226:227]
	v_cvt_pk_bf16_f32 v141, v72, v73
	ds_read_b64_tr_b16 v[70:71], v240 offset:33792
	ds_read_b64_tr_b16 v[72:73], v240 offset:34304
	v_mfma_f32_32x32x16_bf16 v[114:129], v[214:217], v[130:133], v[114:129]
	v_pk_add_f32 v[226:227], v[74:75], v[226:227]
	v_cvt_pk_bf16_f32 v134, v74, v75
	v_pk_add_f32 v[226:227], v[76:77], v[226:227]
	v_cvt_pk_bf16_f32 v135, v76, v77
	ds_read_b64_tr_b16 v[74:75], v240 offset:34816
	ds_read_b64_tr_b16 v[76:77], v240 offset:35328
	v_mfma_f32_32x32x16_bf16 v[98:113], v[194:197], v[130:133], v[98:113]
	v_pk_add_f32 v[226:227], v[78:79], v[226:227]
	v_cvt_pk_bf16_f32 v136, v78, v79
	v_pk_add_f32 v[226:227], v[80:81], v[226:227]
	v_cvt_pk_bf16_f32 v137, v80, v81
	ds_read_b64_tr_b16 v[78:79], v240 offset:35840
	ds_read_b64_tr_b16 v[80:81], v240 offset:36352
	v_add_u32_e32 v162, s16, v241
	ds_read_b128 v[206:209], v162
	ds_read_b128 v[210:213], v162 offset:512
	ds_read_b128 v[202:205], v162 offset:2048
	ds_read_b128 v[198:201], v162 offset:2560
	ds_read_b128 v[222:225], v162 offset:4096
	ds_read_b128 v[218:221], v162 offset:4608
	ds_read_b128 v[214:217], v162 offset:6144
	ds_read_b128 v[194:197], v162 offset:6656
	s_waitcnt lgkmcnt(14)
	v_mfma_f32_32x32x16_bf16 v[2:17], v[158:161], v[66:69], v[2:17]
	v_exp_f32_e32 v114, v114
	v_exp_f32_e32 v115, v115
	v_exp_f32_e32 v116, v116
	v_exp_f32_e32 v117, v117
	s_waitcnt lgkmcnt(14)
	v_mfma_f32_32x32x16_bf16 v[18:33], v[158:161], v[82:85], v[18:33]
	v_exp_f32_e32 v118, v118
	v_exp_f32_e32 v119, v119
	v_exp_f32_e32 v120, v120
	v_exp_f32_e32 v121, v121
	s_waitcnt lgkmcnt(12)
	v_mfma_f32_32x32x16_bf16 v[2:17], v[154:157], v[70:73], v[2:17]
	v_exp_f32_e32 v122, v122
	v_exp_f32_e32 v123, v123
	v_exp_f32_e32 v124, v124
	v_exp_f32_e32 v125, v125
	s_waitcnt lgkmcnt(12)
	v_mfma_f32_32x32x16_bf16 v[18:33], v[154:157], v[86:89], v[18:33]
	v_exp_f32_e32 v126, v126
	v_exp_f32_e32 v127, v127
	v_exp_f32_e32 v128, v128
	v_exp_f32_e32 v129, v129
	s_waitcnt lgkmcnt(10)
	v_mfma_f32_32x32x16_bf16 v[2:17], v[138:141], v[74:77], v[2:17]
	v_exp_f32_e32 v98, v98
	v_exp_f32_e32 v99, v99
	v_exp_f32_e32 v100, v100
	v_exp_f32_e32 v101, v101
	s_waitcnt lgkmcnt(10)
	v_mfma_f32_32x32x16_bf16 v[18:33], v[138:141], v[90:93], v[18:33]
	v_exp_f32_e32 v102, v102
	v_exp_f32_e32 v103, v103
	v_exp_f32_e32 v104, v104
	v_exp_f32_e32 v105, v105
	s_waitcnt lgkmcnt(8)
	v_mfma_f32_32x32x16_bf16 v[2:17], v[134:137], v[78:81], v[2:17]
	v_exp_f32_e32 v106, v106
	v_exp_f32_e32 v107, v107
	v_exp_f32_e32 v108, v108
	v_exp_f32_e32 v109, v109
	s_waitcnt lgkmcnt(8)
	v_mfma_f32_32x32x16_bf16 v[18:33], v[134:137], v[94:97], v[18:33]
	v_exp_f32_e32 v110, v110
	v_exp_f32_e32 v111, v111
	v_exp_f32_e32 v112, v112
	v_exp_f32_e32 v113, v113
	s_waitcnt lgkmcnt(7)
; #define SBAR() __builtin_amdgcn_sched_barrier(0)
;   #define MF(k,q,c) __builtin_amdgcn_mfma_f32_32x32x16_bf16(k,q,c,0,0,0)
;   #define X4(P,B) do{ P[B]=__builtin_amdgcn_exp2f(P[B]); P[B+1]=__builtin_amdgcn_exp2f(P[B+1]); P[B+2]=__builtin_amdgcn_exp2f(P[B+2]); P[B+3]=__builtin_amdgcn_exp2f(P[B+3]); asm volatile("":"+v"(P)); SBAR(); }while(0)
;   #define SP4(SUM,P,B,PW,H) do{ SUM+=P[B]; SUM+=P[B+1]; SUM+=P[B+2]; SUM+=P[B+3]; asm volatile("":"+v"(SUM)); PW[(H)*2]=cvtpk_s(P[B],P[B+1]); PW[(H)*2+1]=cvtpk_s(P[B+2],P[B+3]); asm volatile("":"+v"(PW)); SBAR(); }while(0)
;     #define VLD() do{ _Pragma("unroll") for(int i=0;i<8;++i){ vlo[i]=vtr(vq+((i>>2)*4096+(i&3)*1024)); vhi[i]=vtr(vq+((i>>2)*4096+(i&3)*1024+512)); } }while(0)
;     #define PVB(ks,d0) ob[d0]=MF(__builtin_bit_cast(bf16x8,pb[ks]),VF((ks)+4*(d0)),ob[d0])
; __device__ __forceinline__ void attn_unit2(const bf16*Qu,int qp,const bf16*__restrict__ Kh,int kp,const bf16*__restrict__ Vh,int vp,bf16*Ou,int op,int NT,char*shm,int tid_in){
;     ...
;     if(nx){ a0=MF(kf[0],qa[0],z16); } SP4(sb,b0,0,pb[0],0);  if(nx){ a1=MF(kf[1],qa[0],z16); } SP4(sb,b0,4,pb[0],1);
;     if(nx){ a0=MF(kf[2],qa[1],a0); }  SP4(sb,b0,8,pb[1],0);  if(nx){ a1=MF(kf[3],qa[1],a1); }  SP4(sb,b0,12,pb[1],1);
;     if(nx){ a0=MF(kf[4],qa[2],a0); }  SP4(sb,b1,0,pb[2],0);  if(nx){ a1=MF(kf[5],qa[2],a1); }  SP4(sb,b1,4,pb[2],1);
;     if(nx){ a0=MF(kf[6],qa[3],a0); }  SP4(sb,b1,8,pb[3],0);  if(nx){ a1=MF(kf[7],qa[3],a1); }  SP4(sb,b1,12,pb[3],1);
;     lb+=sb;
;     VLD(); SBAR();
;     PVB(0,0); if(nx) X4(a0,0); PVB(0,1); if(nx) X4(a0,4); PVB(1,0); if(nx) X4(a0,8); PVB(1,1); if(nx) X4(a0,12);
;     PVB(2,0); if(nx) X4(a1,0); PVB(2,1); if(nx) X4(a1,4); PVB(3,0); if(nx) X4(a1,8); PVB(3,1); if(nx) X4(a1,12);
;     SBAR();
;     ...
;     sl_cur=(sl_cur==3*SLOTB)?0:sl_cur+SLOTB; sl_n1=(sl_n1==3*SLOTB)?0:sl_n1+SLOTB; sl_n3=(sl_n3==3*SLOTB)?0:sl_n3+SLOTB;
	v_mfma_f32_32x32x16_bf16 v[82:97], v[206:209], v[170:173], 0
	v_pk_add_f32 v[232:233], v[114:115], v[232:233]
	v_cvt_pk_bf16_f32 v162, v114, v115
	v_pk_add_f32 v[232:233], v[116:117], v[232:233]
	v_cvt_pk_bf16_f32 v163, v116, v117
	ds_read_b64_tr_b16 v[114:115], v240 offset:36864
	ds_read_b64_tr_b16 v[116:117], v240 offset:37376
	s_waitcnt lgkmcnt(8)
	v_mfma_f32_32x32x16_bf16 v[66:81], v[210:213], v[170:173], 0
	v_pk_add_f32 v[232:233], v[118:119], v[232:233]
	v_cvt_pk_bf16_f32 v164, v118, v119
	v_pk_add_f32 v[232:233], v[120:121], v[232:233]
	v_cvt_pk_bf16_f32 v165, v120, v121
	ds_read_b64_tr_b16 v[118:119], v240 offset:37888
	ds_read_b64_tr_b16 v[120:121], v240 offset:38400
	s_waitcnt lgkmcnt(9)
	v_mfma_f32_32x32x16_bf16 v[82:97], v[202:205], v[174:177], v[82:97]
	v_pk_add_f32 v[232:233], v[122:123], v[232:233]
	v_cvt_pk_bf16_f32 v166, v122, v123
	v_pk_add_f32 v[232:233], v[124:125], v[232:233]
	v_cvt_pk_bf16_f32 v167, v124, v125
	ds_read_b64_tr_b16 v[122:123], v240 offset:38912
	ds_read_b64_tr_b16 v[124:125], v240 offset:39424
	s_waitcnt lgkmcnt(10)
	v_mfma_f32_32x32x16_bf16 v[66:81], v[198:201], v[174:177], v[66:81]
	v_pk_add_f32 v[232:233], v[126:127], v[232:233]
	v_cvt_pk_bf16_f32 v168, v126, v127
	v_pk_add_f32 v[232:233], v[128:129], v[232:233]
	v_cvt_pk_bf16_f32 v169, v128, v129
	ds_read_b64_tr_b16 v[126:127], v240 offset:39936
	ds_read_b64_tr_b16 v[128:129], v240 offset:40448
	s_waitcnt lgkmcnt(11)
	v_mfma_f32_32x32x16_bf16 v[82:97], v[222:225], v[178:181], v[82:97]
	v_pk_add_f32 v[232:233], v[98:99], v[232:233]
	v_cvt_pk_bf16_f32 v186, v98, v99
	v_pk_add_f32 v[232:233], v[100:101], v[232:233]
	v_cvt_pk_bf16_f32 v187, v100, v101
	ds_read_b64_tr_b16 v[98:99], v240 offset:32768
	ds_read_b64_tr_b16 v[100:101], v240 offset:33280
	s_waitcnt lgkmcnt(12)
	v_mfma_f32_32x32x16_bf16 v[66:81], v[218:221], v[178:181], v[66:81]
	v_pk_add_f32 v[232:233], v[102:103], v[232:233]
	v_cvt_pk_bf16_f32 v188, v102, v103
	v_pk_add_f32 v[232:233], v[104:105], v[232:233]
	v_cvt_pk_bf16_f32 v189, v104, v105
	ds_read_b64_tr_b16 v[102:103], v240 offset:33792
	ds_read_b64_tr_b16 v[104:105], v240 offset:34304
	s_waitcnt lgkmcnt(13)
	v_mfma_f32_32x32x16_bf16 v[82:97], v[214:217], v[182:185], v[82:97]
	v_pk_add_f32 v[232:233], v[106:107], v[232:233]
	v_cvt_pk_bf16_f32 v190, v106, v107
	v_pk_add_f32 v[232:233], v[108:109], v[232:233]
	v_cvt_pk_bf16_f32 v191, v108, v109
	ds_read_b64_tr_b16 v[106:107], v240 offset:34816
	ds_read_b64_tr_b16 v[108:109], v240 offset:35328
	s_waitcnt lgkmcnt(14)
	v_mfma_f32_32x32x16_bf16 v[66:81], v[194:197], v[182:185], v[66:81]
	v_pk_add_f32 v[232:233], v[110:111], v[232:233]
	v_cvt_pk_bf16_f32 v192, v110, v111
	v_pk_add_f32 v[232:233], v[112:113], v[232:233]
	v_cvt_pk_bf16_f32 v193, v112, v113
	ds_read_b64_tr_b16 v[110:111], v240 offset:35840
	ds_read_b64_tr_b16 v[112:113], v240 offset:36352
	s_waitcnt lgkmcnt(6)
	v_mfma_f32_32x32x16_bf16 v[34:49], v[162:165], v[98:101], v[34:49]
	v_exp_f32_e32 v82, v82
	v_exp_f32_e32 v83, v83
	v_exp_f32_e32 v84, v84
	v_exp_f32_e32 v85, v85
	s_waitcnt lgkmcnt(6)
	v_mfma_f32_32x32x16_bf16 v[50:65], v[162:165], v[114:117], v[50:65]
	v_exp_f32_e32 v86, v86
	v_exp_f32_e32 v87, v87
	v_exp_f32_e32 v88, v88
	v_exp_f32_e32 v89, v89
	s_waitcnt lgkmcnt(4)
	v_mfma_f32_32x32x16_bf16 v[34:49], v[166:169], v[102:105], v[34:49]
	v_exp_f32_e32 v90, v90
	v_exp_f32_e32 v91, v91
	v_exp_f32_e32 v92, v92
	v_exp_f32_e32 v93, v93
	s_waitcnt lgkmcnt(4)
	v_mfma_f32_32x32x16_bf16 v[50:65], v[166:169], v[118:121], v[50:65]
	v_exp_f32_e32 v94, v94
	v_exp_f32_e32 v95, v95
	v_exp_f32_e32 v96, v96
	v_exp_f32_e32 v97, v97
	s_waitcnt lgkmcnt(2)
	v_mfma_f32_32x32x16_bf16 v[34:49], v[186:189], v[106:109], v[34:49]
	v_exp_f32_e32 v66, v66
	v_exp_f32_e32 v67, v67
	v_exp_f32_e32 v68, v68
	v_exp_f32_e32 v69, v69
	s_waitcnt lgkmcnt(2)
	v_mfma_f32_32x32x16_bf16 v[50:65], v[186:189], v[122:125], v[50:65]
	v_exp_f32_e32 v70, v70
	v_exp_f32_e32 v71, v71
	v_exp_f32_e32 v72, v72
	v_exp_f32_e32 v73, v73
	s_waitcnt lgkmcnt(0)
	v_mfma_f32_32x32x16_bf16 v[34:49], v[190:193], v[110:113], v[34:49]
	v_exp_f32_e32 v74, v74
	v_exp_f32_e32 v75, v75
	v_exp_f32_e32 v76, v76
	v_exp_f32_e32 v77, v77
	s_waitcnt lgkmcnt(0)
	v_mfma_f32_32x32x16_bf16 v[50:65], v[190:193], v[126:129], v[50:65]
	v_exp_f32_e32 v78, v78
	v_exp_f32_e32 v79, v79
	v_exp_f32_e32 v80, v80
	v_exp_f32_e32 v81, v81
	s_add_i32 s8, s14, 0x2000
	s_cmpk_lg_i32 s14, 0x6000
	s_cselect_b32 s14, s8, 0
	s_add_i32 s8, s16, 0x2000
	s_cmpk_lg_i32 s16, 0x6000
	s_cselect_b32 s16, s8, 0
	s_add_i32 s8, s15, 0x2000
	s_cmpk_lg_i32 s15, 0x6000
	s_cselect_b32 s15, s8, 0
	s_mov_b64 s[8:9], 0x4000
	v_lshl_add_u64 v[228:229], v[228:229], 0, s[8:9]
	s_cmpk_eq_i32 s13, 0x83
	v_lshl_add_u64 v[230:231], v[230:231], 0, s[8:9]
	s_cbranch_scc1 .LBB0_903

; #define SBAR() __builtin_amdgcn_sched_barrier(0)
;   #define DMA_K(t,slot) glds16(ksrc+(long)(t)*KVBLK*kp,(unsigned)__builtin_amdgcn_readfirstlane(kdst+(slot)))
;   #define DMA_V(t,slot) glds16(vsrc+(long)(t)*KVBLK*vp,(unsigned)__builtin_amdgcn_readfirstlane(vdst+(slot)))
;   #define DMA_K(t,slot) glds16(ksrc+(long)(t)*KVBLK*kp,(unsigned)__builtin_amdgcn_readfirstlane(kdst+(slot)))
;   #define MF(k,q,c) __builtin_amdgcn_mfma_f32_32x32x16_bf16(k,q,c,0,0,0)
; __device__ __forceinline__ void attn_unit2(const bf16*Qu,int qp,const bf16*__restrict__ Kh,int kp,const bf16*__restrict__ Vh,int vp,bf16*Ou,int op,int NT,char*shm,int tid_in){
;     ...
;   for(int t=0;t<NT;++t){
;     if(t>0){ if(t+2<NT) asm volatile("s_waitcnt vmcnt(2) lgkmcnt(0)\n\ts_barrier":::"memory"); else asm volatile("s_waitcnt vmcnt(0) lgkmcnt(0)\n\ts_barrier":::"memory"); }
;     if(t+3<NT){DMA_K(t+3,sl_n3);DMA_V(t+3,sl_n3);}
;     const bool nx=t+1<NT; const lds_cptr vq=vp0+sl_cur; s16x4 vlo[8],vhi[8]; float sa=0.f,sb=0.f;
;     ...
;     b0=MF(kf[0],qb[0],z16); SP4(sa,a0,0,pa[0],0);  b1=MF(kf[1],qb[0],z16); SP4(sa,a0,4,pa[0],1);
;     b0=MF(kf[2],qb[1],b0);  SP4(sa,a0,8,pa[1],0);  b1=MF(kf[3],qb[1],b1);  SP4(sa,a0,12,pa[1],1);
;     b0=MF(kf[4],qb[2],b0);  SP4(sa,a1,0,pa[2],0);  b1=MF(kf[5],qb[2],b1);  SP4(sa,a1,4,pa[2],1);
;     b0=MF(kf[6],qb[3],b0);  SP4(sa,a1,8,pa[3],0);  b1=MF(kf[7],qb[3],b1);  SP4(sa,a1,12,pa[3],1);
;     la+=sa;
;     VLD(); if(nx) kload8(kf,kp0+sl_n1);
;     ...
;     PVA(0,0); X4(b0,0); PVA(0,1); X4(b0,4); PVA(1,0); X4(b0,8); PVA(1,1); X4(b0,12);
;     PVA(2,0); X4(b1,0); PVA(2,1); X4(b1,4); PVA(3,0); X4(b1,8); PVA(3,1); X4(b1,12);
;     if(nx){ a0=MF(kf[0],qa[0],z16); } SP4(sb,b0,0,pb[0],0);  if(nx){ a1=MF(kf[1],qa[0],z16); } SP4(sb,b0,4,pb[0],1);
;     if(nx){ a0=MF(kf[2],qa[1],a0); }  SP4(sb,b0,8,pb[1],0);  if(nx){ a1=MF(kf[3],qa[1],a1); }  SP4(sb,b0,12,pb[1],1);
;     if(nx){ a0=MF(kf[4],qa[2],a0); }  SP4(sb,b1,0,pb[2],0);  if(nx){ a1=MF(kf[5],qa[2],a1); }  SP4(sb,b1,4,pb[2],1);
;     if(nx){ a0=MF(kf[6],qa[3],a0); }  SP4(sb,b1,8,pb[3],0);  if(nx){ a1=MF(kf[7],qa[3],a1); }  SP4(sb,b1,12,pb[3],1);
;     lb+=sb;
;     VLD(); SBAR();
;     PVB(0,0); if(nx) X4(a0,0); PVB(0,1); if(nx) X4(a0,4); PVB(1,0); if(nx) X4(a0,8); PVB(1,1); if(nx) X4(a0,12);
;     PVB(2,0); if(nx) X4(a1,0); PVB(2,1); if(nx) X4(a1,4); PVB(3,0); if(nx) X4(a1,8); PVB(3,1); if(nx) X4(a1,12);
.LBB0_903:
	v_add_u32_e32 v170, s14, v0
	v_add_f32_e32 v0, 0, v82
	s_waitcnt vmcnt(0) lgkmcnt(0)
	s_barrier
	v_add_f32_e32 v0, v83, v0
	v_add_f32_e32 v0, v84, v0
	v_add_f32_e32 v0, v85, v0
	v_cvt_pk_bf16_f32 v158, v82, v83
	v_cvt_pk_bf16_f32 v159, v84, v85
	s_nop 0
	v_add_f32_e32 v0, v86, v0
	v_add_f32_e32 v0, v87, v0
	v_add_f32_e32 v0, v88, v0
	v_add_f32_e32 v0, v89, v0
	v_cvt_pk_bf16_f32 v160, v86, v87
	v_cvt_pk_bf16_f32 v161, v88, v89
	s_nop 0
	v_add_f32_e32 v0, v90, v0
	v_add_f32_e32 v0, v91, v0
	v_add_f32_e32 v0, v92, v0
	v_add_f32_e32 v0, v93, v0
	v_cvt_pk_bf16_f32 v154, v90, v91
	v_cvt_pk_bf16_f32 v155, v92, v93
	s_nop 0
	v_add_f32_e32 v0, v94, v0
	v_add_f32_e32 v0, v95, v0
	v_add_f32_e32 v0, v96, v0
	v_add_f32_e32 v0, v97, v0
	v_cvt_pk_bf16_f32 v156, v94, v95
	v_cvt_pk_bf16_f32 v157, v96, v97
	s_nop 0
	v_add_f32_e32 v0, v66, v0
	v_add_f32_e32 v0, v67, v0
	v_add_f32_e32 v0, v68, v0
	v_add_f32_e32 v0, v69, v0
	v_cvt_pk_bf16_f32 v138, v66, v67
	v_cvt_pk_bf16_f32 v139, v68, v69
	s_nop 0
	v_add_f32_e32 v0, v70, v0
	v_add_f32_e32 v0, v71, v0
	v_add_f32_e32 v0, v72, v0
	v_add_f32_e32 v0, v73, v0
	v_cvt_pk_bf16_f32 v140, v70, v71
	v_cvt_pk_bf16_f32 v141, v72, v73
	s_nop 0
	v_add_f32_e32 v0, v74, v0
	v_add_f32_e32 v0, v75, v0
	v_add_f32_e32 v0, v76, v0
	v_add_f32_e32 v0, v77, v0
	v_cvt_pk_bf16_f32 v134, v74, v75
	v_cvt_pk_bf16_f32 v135, v76, v77
	s_nop 0
	v_add_f32_e32 v0, v78, v0
	v_add_f32_e32 v0, v79, v0
	v_add_f32_e32 v0, v80, v0
	v_add_f32_e32 v0, v81, v0
	v_cvt_pk_bf16_f32 v136, v78, v79
	v_cvt_pk_bf16_f32 v137, v80, v81
	v_mfma_f32_32x32x16_bf16 v[82:97], v[206:209], v[150:153], 0
	ds_read_b64_tr_b16 v[98:99], v170 offset:32768
	ds_read_b64_tr_b16 v[100:101], v170 offset:33280
	ds_read_b64_tr_b16 v[102:103], v170 offset:33792
	ds_read_b64_tr_b16 v[104:105], v170 offset:34304
	ds_read_b64_tr_b16 v[106:107], v170 offset:34816
	ds_read_b64_tr_b16 v[108:109], v170 offset:35328
	ds_read_b64_tr_b16 v[110:111], v170 offset:35840
	ds_read_b64_tr_b16 v[112:113], v170 offset:36352
	ds_read_b64_tr_b16 v[114:115], v170 offset:36864
	ds_read_b64_tr_b16 v[116:117], v170 offset:37376
	ds_read_b64_tr_b16 v[118:119], v170 offset:37888
	ds_read_b64_tr_b16 v[120:121], v170 offset:38400
	ds_read_b64_tr_b16 v[122:123], v170 offset:38912
	ds_read_b64_tr_b16 v[124:125], v170 offset:39424
	ds_read_b64_tr_b16 v[126:127], v170 offset:39936
	ds_read_b64_tr_b16 v[128:129], v170 offset:40448
	v_add_f32_e32 v0, v226, v0
	v_add_f32_e32 v0, v227, v0
	v_mfma_f32_32x32x16_bf16 v[66:81], v[210:213], v[150:153], 0
	v_mfma_f32_32x32x16_bf16 v[82:97], v[202:205], v[146:149], v[82:97]
	v_mfma_f32_32x32x16_bf16 v[66:81], v[198:201], v[146:149], v[66:81]
	v_mfma_f32_32x32x16_bf16 v[82:97], v[222:225], v[142:145], v[82:97]
	v_mfma_f32_32x32x16_bf16 v[66:81], v[218:221], v[142:145], v[66:81]
	v_mfma_f32_32x32x16_bf16 v[82:97], v[214:217], v[130:133], v[82:97]
	v_mfma_f32_32x32x16_bf16 v[66:81], v[194:197], v[130:133], v[66:81]
	s_nop 10
	v_exp_f32_e32 v82, v82
	v_exp_f32_e32 v83, v83
	v_exp_f32_e32 v84, v84
	v_exp_f32_e32 v85, v85
	s_waitcnt lgkmcnt(14)
	v_mfma_f32_32x32x16_bf16 v[2:17], v[158:161], v[98:101], v[2:17]
	s_waitcnt lgkmcnt(6)
	v_mfma_f32_32x32x16_bf16 v[18:33], v[158:161], v[114:117], v[18:33]
	v_exp_f32_e32 v86, v86
	v_exp_f32_e32 v87, v87
	v_exp_f32_e32 v88, v88
	v_exp_f32_e32 v89, v89
	v_mfma_f32_32x32x16_bf16 v[2:17], v[154:157], v[102:105], v[2:17]
	v_exp_f32_e32 v90, v90
	v_exp_f32_e32 v91, v91
	v_exp_f32_e32 v92, v92
	v_exp_f32_e32 v93, v93
	s_waitcnt lgkmcnt(4)
	v_mfma_f32_32x32x16_bf16 v[18:33], v[154:157], v[118:121], v[18:33]
	v_exp_f32_e32 v94, v94
	v_exp_f32_e32 v95, v95
	v_exp_f32_e32 v96, v96
	v_exp_f32_e32 v97, v97
	v_mfma_f32_32x32x16_bf16 v[2:17], v[138:141], v[106:109], v[2:17]
	v_exp_f32_e32 v66, v66
	v_exp_f32_e32 v67, v67
	v_exp_f32_e32 v68, v68
	v_exp_f32_e32 v69, v69
	s_waitcnt lgkmcnt(2)
	v_mfma_f32_32x32x16_bf16 v[18:33], v[138:141], v[122:125], v[18:33]
	v_exp_f32_e32 v70, v70
	v_exp_f32_e32 v71, v71
	v_exp_f32_e32 v72, v72
	v_exp_f32_e32 v73, v73
	v_mfma_f32_32x32x16_bf16 v[2:17], v[134:137], v[110:113], v[2:17]
	v_exp_f32_e32 v74, v74
	v_exp_f32_e32 v75, v75
	v_exp_f32_e32 v76, v76
	v_exp_f32_e32 v77, v77
	s_waitcnt lgkmcnt(0)
	v_mfma_f32_32x32x16_bf16 v[18:33], v[134:137], v[126:129], v[18:33]
	v_exp_f32_e32 v78, v78
	v_exp_f32_e32 v79, v79
	v_exp_f32_e32 v80, v80
	v_exp_f32_e32 v81, v81
	v_add_f32_e32 v98, 0, v82
	v_add_f32_e32 v98, v83, v98
	v_add_f32_e32 v98, v84, v98
	v_add_f32_e32 v98, v85, v98
	v_cvt_pk_bf16_f32 v162, v82, v83
	v_cvt_pk_bf16_f32 v163, v84, v85
	s_nop 0
	v_add_f32_e32 v82, v86, v98
	v_add_f32_e32 v82, v87, v82
	v_add_f32_e32 v82, v88, v82
	v_add_f32_e32 v82, v89, v82
	v_cvt_pk_bf16_f32 v164, v86, v87
	v_cvt_pk_bf16_f32 v165, v88, v89
	s_nop 0
	v_add_f32_e32 v82, v90, v82
	v_add_f32_e32 v82, v91, v82
	v_add_f32_e32 v82, v92, v82
	v_add_f32_e32 v82, v93, v82
	v_cvt_pk_bf16_f32 v166, v90, v91
	v_cvt_pk_bf16_f32 v167, v92, v93
	s_nop 0
	v_add_f32_e32 v82, v94, v82
	v_add_f32_e32 v82, v95, v82
	v_add_f32_e32 v82, v96, v82
	v_add_f32_e32 v82, v97, v82
	v_cvt_pk_bf16_f32 v168, v94, v95
	v_cvt_pk_bf16_f32 v169, v96, v97
	s_nop 0
	v_add_f32_e32 v82, v66, v82
	v_add_f32_e32 v82, v67, v82
	v_add_f32_e32 v82, v68, v82
	v_add_f32_e32 v82, v69, v82
	v_cvt_pk_bf16_f32 v186, v66, v67
	v_cvt_pk_bf16_f32 v187, v68, v69
	s_nop 0
	v_add_f32_e32 v66, v70, v82
	v_add_f32_e32 v66, v71, v66
	v_add_f32_e32 v66, v72, v66
	v_add_f32_e32 v66, v73, v66
	v_cvt_pk_bf16_f32 v188, v70, v71
	v_cvt_pk_bf16_f32 v189, v72, v73
	s_nop 0
	v_add_f32_e32 v66, v74, v66
	v_add_f32_e32 v66, v75, v66
	v_add_f32_e32 v66, v76, v66
	v_add_f32_e32 v66, v77, v66
	v_cvt_pk_bf16_f32 v190, v74, v75
	v_cvt_pk_bf16_f32 v191, v76, v77
	s_nop 0
	v_add_f32_e32 v66, v78, v66
	v_add_f32_e32 v66, v79, v66
	v_add_f32_e32 v66, v80, v66
	v_add_f32_e32 v66, v81, v66
	v_cvt_pk_bf16_f32 v192, v78, v79
	v_cvt_pk_bf16_f32 v193, v80, v81
	ds_read_b64_tr_b16 v[68:69], v170 offset:32768
	ds_read_b64_tr_b16 v[70:71], v170 offset:33280
	ds_read_b64_tr_b16 v[72:73], v170 offset:33792
	ds_read_b64_tr_b16 v[74:75], v170 offset:34304
	ds_read_b64_tr_b16 v[76:77], v170 offset:34816
	ds_read_b64_tr_b16 v[78:79], v170 offset:35328
	ds_read_b64_tr_b16 v[80:81], v170 offset:35840
	ds_read_b64_tr_b16 v[82:83], v170 offset:36352
	ds_read_b64_tr_b16 v[84:85], v170 offset:36864
	ds_read_b64_tr_b16 v[86:87], v170 offset:37376
	ds_read_b64_tr_b16 v[88:89], v170 offset:37888
	ds_read_b64_tr_b16 v[90:91], v170 offset:38400
	ds_read_b64_tr_b16 v[92:93], v170 offset:38912
	ds_read_b64_tr_b16 v[94:95], v170 offset:39424
	ds_read_b64_tr_b16 v[96:97], v170 offset:39936
	ds_read_b64_tr_b16 v[98:99], v170 offset:40448
	s_waitcnt lgkmcnt(14)
; __device__ __forceinline__ int crow(int r,int hi){return (r&3)+8*(r>>2)+4*hi;}
;   #define X4(P,B) do{ P[B]=__builtin_amdgcn_exp2f(P[B]); P[B+1]=__builtin_amdgcn_exp2f(P[B+1]); P[B+2]=__builtin_amdgcn_exp2f(P[B+2]); P[B+3]=__builtin_amdgcn_exp2f(P[B+3]); asm volatile("":"+v"(P)); SBAR(); }while(0)
;     #define PVB(ks,d0) ob[d0]=MF(__builtin_bit_cast(bf16x8,pb[ks]),VF((ks)+4*(d0)),ob[d0])
; __device__ __forceinline__ void attn_unit2(const bf16*Qu,int qp,const bf16*__restrict__ Kh,int kp,const bf16*__restrict__ Vh,int vp,bf16*Ou,int op,int NT,char*shm,int tid_in){
;     ...
;     PVB(0,0); if(nx) X4(a0,0); PVB(0,1); if(nx) X4(a0,4); PVB(1,0); if(nx) X4(a0,8); PVB(1,1); if(nx) X4(a0,12);
;     PVB(2,0); if(nx) X4(a1,0); PVB(2,1); if(nx) X4(a1,4); PVB(3,0); if(nx) X4(a1,8); PVB(3,1); if(nx) X4(a1,12);
;     ...
;   bf16*stg=(bf16*)(shm+U2_OST)+wid*2048;
;   #pragma unroll
;   for(int blk=0;blk<2;++blk){ float l_reg=blk?lb:la; const f32x16 o0=blk?ob[0]:oa[0], o1=blk?ob[1]:oa[1];
;     {auto rr=__builtin_amdgcn_permlane32_swap(__float_as_uint(l_reg),__float_as_uint(l_reg),false,false);l_reg=__uint_as_float(rr[0])+__uint_as_float(rr[1]);}
;     if(hi==0)wsf[32+r32]=l_reg;asm volatile("s_waitcnt lgkmcnt(0)":::"memory");
;     float rli[16];
;     #pragma unroll
;     for(int r=0;r<16;++r)rli[r]=__builtin_amdgcn_rcpf(wsf[32+crow(r,hi)]);
;     #pragma unroll
;     for(int r=0;r<16;++r){const int orow=crow(r,hi); stg[orow*64+r32]=__float2bfloat16(o0[r]*rli[r]); stg[orow*64+32+r32]=__float2bfloat16(o1[r]*rli[r]);}
;     asm volatile("s_waitcnt lgkmcnt(0)":::"memory");
;     bf16*Ow=Ou+(long)(wid*64+blk*32)*op;
;     #pragma unroll
;     for(int i=0;i<4;++i){const int row=i*8+(lane>>3),ch=lane&7; const u32x4 v=*(const u32x4*)(stg+row*64+ch*8); ATTN_STORE16(Ow+(long)row*op+ch*8,v);}
;     asm volatile("s_waitcnt lgkmcnt(0)":::"memory"); }
	v_mfma_f32_32x32x16_bf16 v[34:49], v[162:165], v[68:71], v[34:49]
	s_waitcnt lgkmcnt(6)
	v_mfma_f32_32x32x16_bf16 v[50:65], v[162:165], v[84:87], v[50:65]
	v_mfma_f32_32x32x16_bf16 v[34:49], v[166:169], v[72:75], v[34:49]
	s_waitcnt lgkmcnt(4)
	v_mfma_f32_32x32x16_bf16 v[50:65], v[166:169], v[88:91], v[50:65]
	v_mfma_f32_32x32x16_bf16 v[34:49], v[186:189], v[76:79], v[34:49]
	s_waitcnt lgkmcnt(2)
	v_mfma_f32_32x32x16_bf16 v[50:65], v[186:189], v[92:95], v[50:65]
	v_mfma_f32_32x32x16_bf16 v[34:49], v[190:193], v[80:83], v[34:49]
	s_waitcnt lgkmcnt(0)
	v_mfma_f32_32x32x16_bf16 v[50:65], v[190:193], v[96:99], v[50:65]
	s_lshl_b32 s3, s2, 2
	s_add_i32 s3, s3, 0
	s_add_i32 s3, s3, 0x10000
	v_mov_b32_e32 v67, v0
	v_cmp_gt_u32_e32 vcc, 32, v249
	v_lshl_add_u32 v68, v251, 2, s3
	v_permlane32_swap_b32_e32 v0, v67
	s_and_saveexec_b64 s[8:9], vcc
	v_add_f32_e32 v0, v0, v67
	ds_write_b32 v68, v0 offset:128
	s_or_b64 exec, exec, s[8:9]
	v_add_f32_e32 v70, v232, v66
	v_add_f32_e32 v70, v233, v70
	v_lshlrev_b32_e32 v66, 4, v238
	s_waitcnt lgkmcnt(0)
	v_add_u32_e32 v69, s3, v66
	ds_read_b128 v[72:75], v69 offset:128
	ds_read_b128 v[76:79], v69 offset:160
	s_add_u32 s6, s50, s6
	s_addc_u32 s7, s51, s7
	s_lshl_b32 s8, s10, 1
	s_add_u32 s6, s6, s8
	s_waitcnt lgkmcnt(1)
	v_rcp_f32_e32 v83, v72
	v_rcp_f32_e32 v84, v73
	s_addc_u32 s7, s7, 0
	s_lshl_b32 s8, s11, 12
	s_add_i32 s8, s8, 0
	s_add_i32 s8, s8, 0x10800
	v_lshl_add_u32 v80, v251, 1, s8
	v_lshlrev_b32_e32 v81, 9, v238
	v_rcp_f32_e32 v85, v74
	v_mul_f32_e32 v2, v2, v83
	v_mul_f32_e32 v3, v3, v84
	v_cvt_pk_bf16_f32 v91, v2, s0
	v_add_u32_e32 v2, v80, v81
	v_cvt_pk_bf16_f32 v3, v3, s0
	v_rcp_f32_e32 v86, v75
	s_waitcnt lgkmcnt(0)
	v_rcp_f32_e32 v87, v76
	ds_read_b128 v[72:75], v69 offset:192
	v_rcp_f32_e32 v88, v77
	v_rcp_f32_e32 v89, v78
	v_rcp_f32_e32 v90, v79
	ds_read_b128 v[76:79], v69 offset:224
	ds_write_b16 v2, v3 offset:128
	v_mul_f32_e32 v3, v19, v84
	v_cvt_pk_bf16_f32 v3, v3, s0
	ds_write_b16 v2, v3 offset:192
	v_mul_f32_e32 v3, v4, v85
	v_cvt_pk_bf16_f32 v3, v3, s0
	ds_write_b16 v2, v3 offset:256
	v_mul_f32_e32 v3, v20, v85
	v_cvt_pk_bf16_f32 v3, v3, s0
	ds_write_b16 v2, v3 offset:320
	v_mul_f32_e32 v3, v5, v86
	v_cvt_pk_bf16_f32 v3, v3, s0
	ds_write_b16 v2, v3 offset:384
	v_mul_f32_e32 v3, v21, v86
	v_cvt_pk_bf16_f32 v3, v3, s0
	ds_write_b16 v2, v3 offset:448
	v_mul_f32_e32 v3, v6, v87
	v_cvt_pk_bf16_f32 v3, v3, s0
	ds_write_b16 v2, v3 offset:1024
	v_mul_f32_e32 v3, v22, v87
	v_cvt_pk_bf16_f32 v3, v3, s0
	ds_write_b16 v2, v3 offset:1088
	v_mul_f32_e32 v3, v7, v88
	v_cvt_pk_bf16_f32 v3, v3, s0
	ds_write_b16 v2, v3 offset:1152
	v_mul_f32_e32 v3, v23, v88
	v_cvt_pk_bf16_f32 v3, v3, s0
	ds_write_b16 v2, v3 offset:1216
	v_mul_f32_e32 v3, v8, v89
	v_cvt_pk_bf16_f32 v3, v3, s0
	ds_write_b16 v2, v3 offset:1280
	v_mul_f32_e32 v3, v24, v89
	v_cvt_pk_bf16_f32 v3, v3, s0
	s_waitcnt lgkmcnt(12)
	v_rcp_f32_e32 v72, v72
	ds_write_b16 v2, v3 offset:1344
	v_mul_f32_e32 v3, v9, v90
	v_cvt_pk_bf16_f32 v3, v3, s0
	ds_write_b16 v2, v3 offset:1408
	v_mul_f32_e32 v3, v25, v90
	v_cvt_pk_bf16_f32 v3, v3, s0
	v_rcp_f32_e32 v73, v73
	ds_write_b16 v2, v3 offset:1472
	v_mul_f32_e32 v3, v10, v72
	v_cvt_pk_bf16_f32 v3, v3, s0
	ds_write_b16 v2, v3 offset:2048
	v_mul_f32_e32 v3, v26, v72
	v_cvt_pk_bf16_f32 v3, v3, s0
	v_rcp_f32_e32 v74, v74
	ds_write_b16 v2, v3 offset:2112
	v_mul_f32_e32 v3, v11, v73
	v_cvt_pk_bf16_f32 v3, v3, s0
	ds_write_b16 v2, v3 offset:2176
	v_mul_f32_e32 v3, v27, v73
	v_cvt_pk_bf16_f32 v3, v3, s0
	v_rcp_f32_e32 v75, v75
	ds_write_b16 v2, v3 offset:2240
	v_mul_f32_e32 v3, v12, v74
	v_cvt_pk_bf16_f32 v3, v3, s0
	ds_write_b16 v2, v3 offset:2304
	v_mul_f32_e32 v3, v28, v74
	v_cvt_pk_bf16_f32 v3, v3, s0
	s_waitcnt lgkmcnt(14)
	v_rcp_f32_e32 v76, v76
	ds_write_b16 v2, v3 offset:2368
	v_mul_f32_e32 v3, v13, v75
	v_cvt_pk_bf16_f32 v3, v3, s0
	ds_write_b16 v2, v3 offset:2432
	v_mul_f32_e32 v3, v29, v75
	v_cvt_pk_bf16_f32 v3, v3, s0
	v_rcp_f32_e32 v77, v77
	ds_write_b16 v2, v3 offset:2496
	v_mul_f32_e32 v3, v14, v76
	v_cvt_pk_bf16_f32 v3, v3, s0
	ds_write_b16 v2, v3 offset:3072
	v_mul_f32_e32 v3, v30, v76
	v_cvt_pk_bf16_f32 v3, v3, s0
	v_rcp_f32_e32 v78, v78
	ds_write_b16 v2, v3 offset:3136
	v_mul_f32_e32 v3, v15, v77
	v_cvt_pk_bf16_f32 v3, v3, s0
	ds_write_b16 v2, v3 offset:3200
	v_mul_f32_e32 v3, v31, v77
	v_cvt_pk_bf16_f32 v3, v3, s0
	v_rcp_f32_e32 v79, v79
	ds_write_b16 v2, v3 offset:3264
	v_mul_f32_e32 v3, v16, v78
	v_cvt_pk_bf16_f32 v3, v3, s0
	ds_write_b16 v2, v3 offset:3328
	v_mul_f32_e32 v3, v32, v78
	v_cvt_pk_bf16_f32 v3, v3, s0
	ds_write_b16 v2, v3 offset:3392
	v_mul_f32_e32 v3, v17, v79
	v_cvt_pk_bf16_f32 v3, v3, s0
	v_lshlrev_b32_e32 v0, 1, v248
	v_mul_f32_e32 v18, v18, v83
	ds_write_b16 v2, v3 offset:3456
	v_mul_f32_e32 v3, v33, v79
	v_lshrrev_b32_e32 v71, 3, v249
	v_and_b32_e32 v0, 0x70, v0
	v_cvt_pk_bf16_f32 v18, v18, s0
	v_cvt_pk_bf16_f32 v3, v3, s0
	v_add_u32_e32 v82, s8, v0
	v_lshl_add_u64 v[66:67], s[6:7], 0, v[0:1]
	v_lshlrev_b32_e32 v0, 7, v71
	ds_write_b16 v2, v91
	ds_write_b16 v2, v18 offset:64
	ds_write_b16 v2, v3 offset:3520
	v_or_b32_e32 v7, 8, v71
	s_waitcnt lgkmcnt(0)
	v_add_u32_e32 v3, v82, v0
	v_lshlrev_b32_e32 v4, 7, v7
	ds_read_b128 v[8:11], v3
	v_add_u32_e32 v4, v82, v4
	ds_read_b128 v[12:15], v4
	v_lshl_add_u64 v[18:19], v[66:67], 0, s[4:5]
	v_lshlrev_b32_e32 v0, 10, v71
	v_lshl_add_u64 v[16:17], v[18:19], 0, v[0:1]
	v_lshlrev_b32_e32 v0, 10, v7
	s_waitcnt lgkmcnt(1)
	global_store_dwordx4 v[16:17], v[8:11], off
	s_nop 1
	v_lshl_add_u64 v[8:9], v[18:19], 0, v[0:1]
	s_waitcnt lgkmcnt(0)
; __device__ __forceinline__ void attn_unit2(const bf16*Qu,int qp,const bf16*__restrict__ Kh,int kp,const bf16*__restrict__ Vh,int vp,bf16*Ou,int op,int NT,char*shm,int tid_in){
;     ...
;   for(int blk=0;blk<2;++blk){ float l_reg=blk?lb:la; const f32x16 o0=blk?ob[0]:oa[0], o1=blk?ob[1]:oa[1];
;     {auto rr=__builtin_amdgcn_permlane32_swap(__float_as_uint(l_reg),__float_as_uint(l_reg),false,false);l_reg=__uint_as_float(rr[0])+__uint_as_float(rr[1]);}
;     if(hi==0)wsf[32+r32]=l_reg;asm volatile("s_waitcnt lgkmcnt(0)":::"memory");
;     float rli[16];
;     #pragma unroll
;     for(int r=0;r<16;++r)rli[r]=__builtin_amdgcn_rcpf(wsf[32+crow(r,hi)]);
;     #pragma unroll
;     for(int r=0;r<16;++r){const int orow=crow(r,hi); stg[orow*64+r32]=__float2bfloat16(o0[r]*rli[r]); stg[orow*64+32+r32]=__float2bfloat16(o1[r]*rli[r]);}
;     asm volatile("s_waitcnt lgkmcnt(0)":::"memory");
;     bf16*Ow=Ou+(long)(wid*64+blk*32)*op;
;     #pragma unroll
;     for(int i=0;i<4;++i){const int row=i*8+(lane>>3),ch=lane&7; const u32x4 v=*(const u32x4*)(stg+row*64+ch*8); ATTN_STORE16(Ow+(long)row*op+ch*8,v);}
;     asm volatile("s_waitcnt lgkmcnt(0)":::"memory"); }
;   asm volatile("s_waitcnt lgkmcnt(0)\n\ts_barrier":::"memory");
; __device__ __forceinline__ CvItem cv_make(CArgs a, unsigned char* ws, int l, int it, int lane) {
;     CvItem c; const int which = it / 11008, r = it % 11008, e = r / 688, q = r % 688;
;     if (which < 2) { const int kb = q / 43, nb = q % 43, n0 = nb * 64, k0 = kb * 64;
;         const float* W = inp(a, which == 0 ? I_WG : I_WU) + ((size_t)(l * NE + e) * D) * FF;
;         const int drow = e * 5632 + (n0 >> 7) * 256 + (n0 & 127) + which * 128; unsigned char* d0 = ws + WS_WGU + (size_t)drow * D + k0;
;         c.src = W + (size_t)k0 * FF + n0; c.voff = (unsigned)((lane >> 4) * FF + 4 * (lane & 15)) * 4u; c.ldw = FF; c.d0 = d0; c.d1 = d0 + (size_t)32 * D; c.pitch = D; c.scale = WSC_GU; }
;     else { const int kb = q / 16, nb = q % 16, n0 = nb * 64, k0 = kb * 64;
;         const float* W = inp(a, I_WDN) + ((size_t)(l * NE + e) * FF) * D; unsigned char* d0 = ws + WS_WD + ((size_t)e * D + n0) * FFP + k0;
;         c.src = W + (size_t)k0 * D + n0; c.voff = (unsigned)((lane >> 4) * D + 4 * (lane & 15)) * 4u; c.ldw = D; c.d0 = d0; c.d1 = d0 + (size_t)32 * FFP; c.pitch = FFP; c.scale = WSC_D; }
	global_store_dwordx4 v[8:9], v[12:15], off
	v_or_b32_e32 v8, 16, v71
	v_lshlrev_b32_e32 v0, 7, v8
	v_or_b32_e32 v9, 24, v71
	v_add_u32_e32 v5, v82, v0
	v_lshlrev_b32_e32 v6, 7, v9
	ds_read_b128 v[10:13], v5
	v_add_u32_e32 v6, v82, v6
	ds_read_b128 v[14:17], v6
	v_lshlrev_b32_e32 v0, 10, v8
	v_lshl_add_u64 v[20:21], v[18:19], 0, v[0:1]
	v_lshlrev_b32_e32 v0, 10, v9
	s_waitcnt lgkmcnt(1)
	global_store_dwordx4 v[20:21], v[10:13], off
	s_nop 1
	v_lshl_add_u64 v[10:11], v[18:19], 0, v[0:1]
	s_waitcnt lgkmcnt(0)
	global_store_dwordx4 v[10:11], v[14:17], off
	s_waitcnt lgkmcnt(0)
	v_mov_b32_e32 v0, v70
	s_nop 1
	v_permlane32_swap_b32_e32 v70, v0
	s_mov_b64 s[4:5], exec
	s_and_b64 s[6:7], s[4:5], vcc
	v_mov_b32_e32 v238, v239
	v_mov_b32_e32 v241, 0x358637bd
	v_mov_b32_e32 v239, 0x3727c5ac
	v_mov_b32_e32 v240, 0x7f800000
	s_mov_b64 exec, s[6:7]
	v_add_f32_e32 v0, v70, v0
	ds_write_b32 v68, v0 offset:128
	s_or_b64 exec, exec, s[4:5]
	s_waitcnt lgkmcnt(0)
	ds_read_b128 v[10:13], v69 offset:128
	ds_read_b128 v[14:17], v69 offset:160
	v_lshlrev_b32_e32 v18, 9, v8
	v_lshlrev_b32_e32 v19, 9, v9
	s_or_b32 s2, s2, 32
	s_waitcnt lgkmcnt(1)
	v_rcp_f32_e32 v20, v10
	v_rcp_f32_e32 v21, v11
	v_rcp_f32_e32 v22, v12
	v_rcp_f32_e32 v23, v13
	v_mul_f32_e32 v26, v34, v20
	v_mul_f32_e32 v20, v50, v20
	v_cvt_pk_bf16_f32 v20, v20, s0
	s_waitcnt lgkmcnt(0)
	v_rcp_f32_e32 v24, v14
	ds_read_b128 v[8:11], v69 offset:192
	v_rcp_f32_e32 v25, v15
	ds_read_b128 v[12:15], v69 offset:224
	ds_write_b16 v2, v20 offset:64
	v_mul_f32_e32 v20, v35, v21
	v_cvt_pk_bf16_f32 v20, v20, s0
	ds_write_b16 v2, v20 offset:128
	v_mul_f32_e32 v20, v51, v21
	v_cvt_pk_bf16_f32 v20, v20, s0
	ds_write_b16 v2, v20 offset:192
	v_mul_f32_e32 v20, v36, v22
	v_cvt_pk_bf16_f32 v20, v20, s0
	ds_write_b16 v2, v20 offset:256
	v_mul_f32_e32 v20, v52, v22
	v_cvt_pk_bf16_f32 v20, v20, s0
	ds_write_b16 v2, v20 offset:320
	v_mul_f32_e32 v20, v37, v23
	v_cvt_pk_bf16_f32 v20, v20, s0
	ds_write_b16 v2, v20 offset:384
	v_mul_f32_e32 v20, v53, v23
	v_cvt_pk_bf16_f32 v20, v20, s0
	ds_write_b16 v2, v20 offset:448
	v_mul_f32_e32 v20, v38, v24
	v_cvt_pk_bf16_f32 v20, v20, s0
	ds_write_b16 v2, v20 offset:1024
	v_mul_f32_e32 v20, v54, v24
	v_cvt_pk_bf16_f32 v20, v20, s0
	v_rcp_f32_e32 v16, v16
	ds_write_b16 v2, v20 offset:1088
	v_mul_f32_e32 v20, v39, v25
	v_cvt_pk_bf16_f32 v20, v20, s0
	v_rcp_f32_e32 v17, v17
	ds_write_b16 v2, v20 offset:1152
	v_mul_f32_e32 v20, v55, v25
	v_cvt_pk_bf16_f32 v20, v20, s0
	ds_write_b16 v2, v20 offset:1216
	v_mul_f32_e32 v20, v40, v16
	v_mul_f32_e32 v16, v56, v16
	v_cvt_pk_bf16_f32 v16, v16, s0
	s_waitcnt lgkmcnt(12)
	v_rcp_f32_e32 v8, v8
	ds_write_b16 v2, v16 offset:1344
	v_mul_f32_e32 v16, v41, v17
	v_cvt_pk_bf16_f32 v16, v16, s0
	v_rcp_f32_e32 v9, v9
	ds_write_b16 v2, v16 offset:1408
	v_mul_f32_e32 v16, v57, v17
	v_cvt_pk_bf16_f32 v16, v16, s0
	ds_write_b16 v2, v16 offset:1472
	v_mul_f32_e32 v16, v42, v8
	v_mul_f32_e32 v8, v58, v8
	v_cvt_pk_bf16_f32 v8, v8, s0
	v_rcp_f32_e32 v10, v10
	ds_write_b16 v2, v8 offset:2112
	v_mul_f32_e32 v8, v43, v9
	v_cvt_pk_bf16_f32 v8, v8, s0
	ds_write_b16 v2, v8 offset:2176
	v_mul_f32_e32 v8, v59, v9
	v_cvt_pk_bf16_f32 v8, v8, s0
	v_rcp_f32_e32 v11, v11
	ds_write_b16 v2, v8 offset:2240
	v_mul_f32_e32 v8, v44, v10
	v_cvt_pk_bf16_f32 v8, v8, s0
	ds_write_b16 v2, v8 offset:2304
	v_mul_f32_e32 v8, v60, v10
	v_cvt_pk_bf16_f32 v8, v8, s0
	s_waitcnt lgkmcnt(14)
	v_rcp_f32_e32 v12, v12
	ds_write_b16 v2, v8 offset:2368
	v_mul_f32_e32 v8, v45, v11
	v_cvt_pk_bf16_f32 v8, v8, s0
	ds_write_b16 v2, v8 offset:2432
	v_mul_f32_e32 v8, v61, v11
	v_cvt_pk_bf16_f32 v8, v8, s0
	v_rcp_f32_e32 v13, v13
	ds_write_b16 v2, v8 offset:2496
	v_mul_f32_e32 v8, v46, v12
	v_cvt_pk_bf16_f32 v8, v8, s0
	ds_write_b16 v2, v8 offset:3072
	v_mul_f32_e32 v8, v62, v12
	v_cvt_pk_bf16_f32 v8, v8, s0
	v_rcp_f32_e32 v14, v14
	ds_write_b16 v2, v8 offset:3136
	v_mul_f32_e32 v8, v47, v13
	v_cvt_pk_bf16_f32 v8, v8, s0
	ds_write_b16 v2, v8 offset:3200
	v_mul_f32_e32 v8, v63, v13
	v_cvt_pk_bf16_f32 v8, v8, s0
	v_rcp_f32_e32 v15, v15
	ds_write_b16 v2, v8 offset:3264
	v_mul_f32_e32 v8, v48, v14
	v_cvt_pk_bf16_f32 v8, v8, s0
	ds_write_b16 v2, v8 offset:3328
	v_mul_f32_e32 v8, v64, v14
	v_cvt_pk_bf16_f32 v8, v8, s0
	ds_write_b16 v2, v8 offset:3392
	v_mul_f32_e32 v8, v49, v15
	v_cvt_pk_bf16_f32 v8, v8, s0
	ds_write_b16 v2, v8 offset:3456
	v_mul_f32_e32 v8, v65, v15
	v_cvt_pk_bf16_f32 v26, v26, s0
	v_cvt_pk_bf16_f32 v20, v20, s0
	v_cvt_pk_bf16_f32 v16, v16, s0
	v_cvt_pk_bf16_f32 v8, v8, s0
	ds_write_b16 v2, v26
	ds_write_b16 v2, v20 offset:1280
	ds_write_b16 v2, v16 offset:2048
	ds_write_b16 v2, v8 offset:3520
	s_waitcnt lgkmcnt(0)
	ds_read_b128 v[8:11], v3
	ds_read_b128 v[12:15], v4
	s_ashr_i32 s3, s2, 31
	v_lshlrev_b32_e32 v0, 9, v71
	s_lshl_b64 s[2:3], s[2:3], 10
	v_lshlrev_b32_e32 v7, 9, v7
	v_lshl_add_u64 v[16:17], v[66:67], 0, s[2:3]
	v_lshlrev_b32_e32 v0, 1, v0
	v_lshl_add_u64 v[2:3], v[16:17], 0, v[0:1]
	v_lshlrev_b32_e32 v0, 1, v7
	s_waitcnt lgkmcnt(1)
	global_store_dwordx4 v[2:3], v[8:11], off
	ds_read_b128 v[2:5], v5
	s_cmp_gt_i32 s47, 11
	v_lshl_add_u64 v[8:9], v[16:17], 0, v[0:1]
	s_waitcnt lgkmcnt(1)
	global_store_dwordx4 v[8:9], v[12:15], off
	ds_read_b128 v[6:9], v6
	v_lshlrev_b32_e32 v0, 1, v18
	v_lshl_add_u64 v[10:11], v[16:17], 0, v[0:1]
	v_lshlrev_b32_e32 v0, 1, v19
	s_waitcnt lgkmcnt(1)
	global_store_dwordx4 v[10:11], v[2:5], off
	s_nop 1
	v_lshl_add_u64 v[2:3], v[16:17], 0, v[0:1]
	s_waitcnt lgkmcnt(0)
	global_store_dwordx4 v[2:3], v[6:9], off
	s_waitcnt lgkmcnt(0)
	s_waitcnt lgkmcnt(0)
	s_barrier
	s_cbranch_scc1 .LBB0_923
	v_readlane_b32 s2, v254, 26
	v_readlane_b32 s3, v254, 27
	s_mul_i32 s12, s47, s2
	v_readlane_b32 s2, v254, 22
	s_add_i32 s12, s12, s2
	v_readlane_b32 s3, v254, 23
	s_mul_hi_i32 s2, s12, 0x2fa0be83
	s_lshr_b32 s3, s2, 31
	s_ashr_i32 s6, s2, 11
	s_add_i32 s6, s6, s3
	s_mul_i32 s2, s6, 0x2b00
	s_sub_i32 s2, s12, s2
	s_mul_i32 s3, s2, 0x2fa1
	s_lshr_b32 s4, s3, 31
	s_ashr_i32 s7, s3, 23
	s_add_i32 s7, s7, s4
	s_mul_i32 s3, s7, 0x2b0
	s_sub_i32 s13, s2, s3
	s_cmpk_gt_i32 s12, 0x55ff
	s_mov_b64 s[4:5], -1
	v_mbcnt_lo_u32_b32 v2, -1, 0
	v_mbcnt_hi_u32_b32 v2, -1, v2
	s_cbranch_scc0 .LBB0_910
	s_and_b32 s2, 0xffff, s13
	s_lshl_b32 s3, s2, 6
	s_and_b32 s10, s3, 0x3c0
	s_lshl_b32 s4, s2, 2
	s_load_dwordx2 s[2:3], s[24:25], 0xc8
	s_and_b32 s11, s4, 0xfc0
	s_add_i32 s4, s67, s7
	s_mov_b32 s5, s87
	s_mul_i32 s4, s4, 0x2b0000
	s_lshl_b64 s[4:5], s[4:5], 2
	s_waitcnt lgkmcnt(0)
	s_add_u32 s2, s2, s4
	s_addc_u32 s3, s3, s5
	s_lshl_b32 s4, s7, 10
	s_or_b32 s4, s10, s4
	s_mulk_i32 s4, 0xb00
	s_add_u32 s4, s68, s4
	s_addc_u32 s5, s69, 0
	s_add_u32 s8, s4, s11
	s_addc_u32 s9, s5, 0
	s_lshl_b32 s4, s11, 12
	s_add_u32 s2, s2, s4
	s_addc_u32 s3, s3, 0
	s_lshl_b32 s4, s10, 2
	s_add_u32 s2, s2, s4
	s_addc_u32 s3, s3, 0
	v_lshlrev_b32_e32 v3, 4, v2
	v_lshlrev_b32_e32 v0, 8, v2
	v_and_b32_e32 v3, 0xf0, v3
	s_movk_i32 s4, 0xf000
	s_add_u32 s10, s8, 0x16000
	v_and_or_b32 v0, v0, s4, v3
	s_addc_u32 s11, s9, 0
	s_mov_b64 s[4:5], 0
